# adds hand-written ConvGLU edge fix-up (batched loads, one wait per batch) on top of the LayerNorm/init row-pass rewrite
# speedup vs baseline: 1.0346x; 1.0009x over previous
; DI int otid() { int t = threadIdx.x; asm volatile("" : "+v"(t)); return t; }
; DI void glu_fix_panel(const Params& p, int l, int pm) {
;     unsigned char* ws = p.ws;
;     bf16_t* G = (bf16_t*)(ws + WS_G);
;     const float* EA = (const float*)(ws + WS_EDGE); const float* EP = EA + (size_t)36 * 4 * DFF; const float* EU = EP + (size_t)36 * 4 * DFF;
;     const float* cw = p.in[17] + (size_t)l * 3 * DFF;
;     const int tid_ = otid();
;     const int pr = pm % 9;
;     for (int it = tid_; it < 4 * (DFF / 4); it += 512) {
;         const int col = (it % (DFF / 4)) * 4, e = it / (DFF / 4);
;         f32x4 nb = (f32x4){0.f, 0.f, 0.f, 0.f}; int tap; int tok;
;         if (e == 0) { tap = 0; tok = 0; if (!(pr == 0 || pr == 1)) nb = *(const f32x4*)(EA + ((size_t)(pm - 1) * 4 + 3) * DFF + col); }
;         else if (e == 1) { tap = 2; tok = 127; nb = *(const f32x4*)(EA + ((size_t)pm * 4 + 2) * DFF + col); }
;         else if (e == 2) { tap = 0; tok = 128; nb = *(const f32x4*)(EA + ((size_t)pm * 4 + 1) * DFF + col); }
;         else { tap = 2; tok = 255; if (!(pr == 0 || pr == 8)) nb = *(const f32x4*)(EA + ((size_t)(pm + 1) * 4 + 0) * DFF + col); }
;         const f32x4 w = *(const f32x4*)(cw + (size_t)tap * DFF + col);
;         const size_t eo = ((size_t)pm * 4 + e) * DFF + col;
;         const f32x4 pp = *(const f32x4*)(EP + eo), uu = *(const f32x4*)(EU + eo);
.LBB0_1601:
	s_andn2_b64 vcc, exec, s[6:7]
	s_cbranch_vccnz .LBB0_1622
	s_mov_b32 s9, s8
	s_mul_i32 s29, s9, 57
	s_lshr_b32 s29, s29, 9
	s_mul_i32 s29, s29, 9
	s_sub_u32 s11, s9, s29
	s_cmp_lt_u32 s11, 2
	s_cselect_b64 s[36:37], -1, 0
	s_cmp_eq_u32 s11, 0
	s_cselect_b64 s[72:73], -1, 0
	s_cmp_eq_u32 s11, 8
	s_cselect_b64 s[54:55], -1, 0
	s_or_b64 s[54:55], s[54:55], s[72:73]
	s_mul_i32 s29, s9, 0x16000
	s_add_u32 s2, s50, 0x116b8000
	s_addc_u32 s3, s51, 0
	s_add_u32 s2, s2, s29
	s_addc_u32 s3, s3, 0
	s_add_u32 s4, s50, 0x119d0000
	s_addc_u32 s5, s51, 0
	s_add_u32 s4, s4, s29
	s_addc_u32 s5, s5, 0
	s_add_u32 s6, s50, 0x113a0000
	s_addc_u32 s7, s51, 0
	s_add_u32 s6, s6, s29
	s_addc_u32 s7, s7, 0
	s_sub_u32 s6, s6, 0x5800
	s_subb_u32 s7, s7, 0
	s_mul_i32 s29, s9, 0x2c0000
	s_add_u32 s22, s50, 0x1d9a0000
	s_addc_u32 s23, s51, 0
	s_add_u32 s22, s22, s29
	s_addc_u32 s23, s23, 0
	s_mov_b32 s27, 0x2e8ba3
	v_mov_b32_e32 v140, v202
	v_mul_hi_u32 v121, v140, s27
	v_mul_u32_u24_e32 v142, 0x580, v121
	v_sub_u32_e32 v141, v140, v142
	v_mul_u32_u24_e32 v142, 0x5800, v121
	v_lshl_add_u32 v145, v141, 4, v142
	v_and_b32_e32 v144, 1, v121
	v_mul_u32_u24_e32 v143, 0xb000, v144
	v_add_u32_e32 v146, v143, v145
	v_add_u32_e32 v148, 0x5800, v145
	v_lshl_add_u32 v147, v141, 4, v143
	v_lshrrev_b32_e32 v149, 1, v121
	v_mul_u32_u24_e32 v149, 0x160000, v149
	v_mul_u32_u24_e32 v150, 0x15d400, v144
	v_lshlrev_b32_e32 v142, 3, v141
	v_add3_u32 v120, v149, v150, v142
	v_cmp_eq_u32_e64 s[72:73], 0, v121
	v_cmp_eq_u32_e64 s[74:75], 3, v121
	s_and_b64 s[72:73], s[72:73], s[36:37]
	s_and_b64 s[74:75], s[74:75], s[54:55]
	s_or_b64 vcc, s[72:73], s[74:75]
	v_cndmask_b32_e32 v146, v146, v148, vcc
	global_load_dwordx4 v[12:15], v146, s[6:7]
	global_load_dwordx4 v[16:19], v147, s[38:39]
	global_load_dwordx4 v[20:23], v145, s[2:3]
	global_load_dwordx4 v[24:27], v145, s[4:5]
	v_add_u32_e32 v140, 0x200, v202
	v_mul_hi_u32 v123, v140, s27
	v_mul_u32_u24_e32 v142, 0x580, v123
	v_sub_u32_e32 v141, v140, v142
	v_mul_u32_u24_e32 v142, 0x5800, v123
	v_lshl_add_u32 v145, v141, 4, v142
	v_and_b32_e32 v144, 1, v123
	v_mul_u32_u24_e32 v143, 0xb000, v144
	v_add_u32_e32 v146, v143, v145
	v_add_u32_e32 v148, 0x5800, v145
	v_lshl_add_u32 v147, v141, 4, v143
	v_lshrrev_b32_e32 v149, 1, v123
	v_mul_u32_u24_e32 v149, 0x160000, v149
	v_mul_u32_u24_e32 v150, 0x15d400, v144
	v_lshlrev_b32_e32 v142, 3, v141
	v_add3_u32 v122, v149, v150, v142
	v_cmp_eq_u32_e64 s[72:73], 0, v123
	v_cmp_eq_u32_e64 s[74:75], 3, v123
	s_and_b64 s[72:73], s[72:73], s[36:37]
	s_and_b64 s[74:75], s[74:75], s[54:55]
	s_or_b64 vcc, s[72:73], s[74:75]
	v_cndmask_b32_e32 v146, v146, v148, vcc
	global_load_dwordx4 v[28:31], v146, s[6:7]
	global_load_dwordx4 v[32:35], v147, s[38:39]
	global_load_dwordx4 v[36:39], v145, s[2:3]
	global_load_dwordx4 v[40:43], v145, s[4:5]
	v_add_u32_e32 v140, 0x400, v202
	v_mul_hi_u32 v125, v140, s27
	v_mul_u32_u24_e32 v142, 0x580, v125
	v_sub_u32_e32 v141, v140, v142
	v_mul_u32_u24_e32 v142, 0x5800, v125
	v_lshl_add_u32 v145, v141, 4, v142
	v_and_b32_e32 v144, 1, v125
	v_mul_u32_u24_e32 v143, 0xb000, v144
	v_add_u32_e32 v146, v143, v145
	v_add_u32_e32 v148, 0x5800, v145
	v_lshl_add_u32 v147, v141, 4, v143
	v_lshrrev_b32_e32 v149, 1, v125
	v_mul_u32_u24_e32 v149, 0x160000, v149
	v_mul_u32_u24_e32 v150, 0x15d400, v144
	v_lshlrev_b32_e32 v142, 3, v141
	v_add3_u32 v124, v149, v150, v142
	v_cmp_eq_u32_e64 s[72:73], 0, v125
	v_cmp_eq_u32_e64 s[74:75], 3, v125
	s_and_b64 s[72:73], s[72:73], s[36:37]
	s_and_b64 s[74:75], s[74:75], s[54:55]
	s_or_b64 vcc, s[72:73], s[74:75]
	v_cndmask_b32_e32 v146, v146, v148, vcc
	global_load_dwordx4 v[44:47], v146, s[6:7]
	global_load_dwordx4 v[48:51], v147, s[38:39]
	global_load_dwordx4 v[52:55], v145, s[2:3]
	global_load_dwordx4 v[56:59], v145, s[4:5]
	v_add_u32_e32 v140, 0x600, v202
	v_mul_hi_u32 v127, v140, s27
	v_mul_u32_u24_e32 v142, 0x580, v127
	v_sub_u32_e32 v141, v140, v142
	v_mul_u32_u24_e32 v142, 0x5800, v127
	v_lshl_add_u32 v145, v141, 4, v142
	v_and_b32_e32 v144, 1, v127
	v_mul_u32_u24_e32 v143, 0xb000, v144
	v_add_u32_e32 v146, v143, v145
	v_add_u32_e32 v148, 0x5800, v145
	v_lshl_add_u32 v147, v141, 4, v143
	v_lshrrev_b32_e32 v149, 1, v127
	v_mul_u32_u24_e32 v149, 0x160000, v149
	v_mul_u32_u24_e32 v150, 0x15d400, v144
	v_lshlrev_b32_e32 v142, 3, v141
	v_add3_u32 v126, v149, v150, v142
	v_cmp_eq_u32_e64 s[72:73], 0, v127
	v_cmp_eq_u32_e64 s[74:75], 3, v127
	s_and_b64 s[72:73], s[72:73], s[36:37]
	s_and_b64 s[74:75], s[74:75], s[54:55]
	s_or_b64 vcc, s[72:73], s[74:75]
	v_cndmask_b32_e32 v146, v146, v148, vcc
	global_load_dwordx4 v[60:63], v146, s[6:7]
	global_load_dwordx4 v[64:67], v147, s[38:39]
	global_load_dwordx4 v[68:71], v145, s[2:3]
	global_load_dwordx4 v[72:75], v145, s[4:5]
	v_add_u32_e32 v140, 0x800, v202
	v_mul_hi_u32 v129, v140, s27
	v_mul_u32_u24_e32 v142, 0x580, v129
	v_sub_u32_e32 v141, v140, v142
	v_mul_u32_u24_e32 v142, 0x5800, v129
	v_lshl_add_u32 v145, v141, 4, v142
	v_and_b32_e32 v144, 1, v129
	v_mul_u32_u24_e32 v143, 0xb000, v144
	v_add_u32_e32 v146, v143, v145
	v_add_u32_e32 v148, 0x5800, v145
	v_lshl_add_u32 v147, v141, 4, v143
	v_lshrrev_b32_e32 v149, 1, v129
	v_mul_u32_u24_e32 v149, 0x160000, v149
	v_mul_u32_u24_e32 v150, 0x15d400, v144
	v_lshlrev_b32_e32 v142, 3, v141
	v_add3_u32 v128, v149, v150, v142
	v_cmp_eq_u32_e64 s[72:73], 0, v129
	v_cmp_eq_u32_e64 s[74:75], 3, v129
	s_and_b64 s[72:73], s[72:73], s[36:37]
	s_and_b64 s[74:75], s[74:75], s[54:55]
	s_or_b64 vcc, s[72:73], s[74:75]
	v_cndmask_b32_e32 v146, v146, v148, vcc
	global_load_dwordx4 v[88:91], v146, s[6:7]
	global_load_dwordx4 v[92:95], v147, s[38:39]
	global_load_dwordx4 v[96:99], v145, s[2:3]
	global_load_dwordx4 v[100:103], v145, s[4:5]
	v_add_u32_e32 v140, 0xa00, v202
	v_mul_hi_u32 v131, v140, s27
	v_mul_u32_u24_e32 v142, 0x580, v131
	v_sub_u32_e32 v141, v140, v142
	v_mul_u32_u24_e32 v142, 0x5800, v131
	v_lshl_add_u32 v145, v141, 4, v142
	v_and_b32_e32 v144, 1, v131
	v_mul_u32_u24_e32 v143, 0xb000, v144
	v_add_u32_e32 v146, v143, v145
	v_add_u32_e32 v148, 0x5800, v145
	v_lshl_add_u32 v147, v141, 4, v143
	v_lshrrev_b32_e32 v149, 1, v131
	v_mul_u32_u24_e32 v149, 0x160000, v149
	v_mul_u32_u24_e32 v150, 0x15d400, v144
	v_lshlrev_b32_e32 v142, 3, v141
	v_add3_u32 v130, v149, v150, v142
	v_cmp_eq_u32_e64 s[72:73], 0, v131
	v_cmp_eq_u32_e64 s[74:75], 3, v131
	s_and_b64 s[72:73], s[72:73], s[36:37]
	s_and_b64 s[74:75], s[74:75], s[54:55]
	s_or_b64 vcc, s[72:73], s[74:75]
	v_cndmask_b32_e32 v146, v146, v148, vcc
	global_load_dwordx4 v[104:107], v146, s[6:7]
	global_load_dwordx4 v[108:111], v147, s[38:39]
	global_load_dwordx4 v[112:115], v145, s[2:3]
	global_load_dwordx4 v[116:119], v145, s[4:5]
	s_waitcnt vmcnt(0)
; DI float silu(float v) { return v * __builtin_amdgcn_rcpf(1.f + __builtin_amdgcn_exp2f(-1.4426950408889634f * v)); }
; DI void st_bf16x4(bf16_t* p, f32x4 v) { u32x2 w; w.x = cvt_pk_bf16(v[0], v[1]); w.y = cvt_pk_bf16(v[2], v[3]); *(u32x2*)p = w; }
; DI void glu_fix_panel(const Params& p, int l, int pm) {
;     ...
;         f32x4 g;
; #pragma unroll
;         for (int j = 0; j < 4; ++j) g[j] = silu(pp[j] + w[j] * nb[j]) * uu[j];
;         st_bf16x4(G + ((size_t)pm * BM + tok) * DFF + col, g);
;     }
	v_cmp_eq_u32_e64 s[72:73], 0, v121
	v_cmp_eq_u32_e64 s[74:75], 3, v121
	s_and_b64 s[72:73], s[72:73], s[36:37]
	s_and_b64 s[74:75], s[74:75], s[54:55]
	s_or_b64 vcc, s[72:73], s[74:75]
	v_cndmask_b32_e64 v12, v12, 0, vcc
	v_cndmask_b32_e64 v13, v13, 0, vcc
	v_cndmask_b32_e64 v14, v14, 0, vcc
	v_cndmask_b32_e64 v15, v15, 0, vcc
	v_fmac_f32_e32 v20, v16, v12
	v_fmac_f32_e32 v21, v17, v13
	v_fmac_f32_e32 v22, v18, v14
	v_fmac_f32_e32 v23, v19, v15
	v_mul_f32_e32 v12, 0xbfb8aa3b, v20
	v_mul_f32_e32 v13, 0xbfb8aa3b, v21
	v_mul_f32_e32 v14, 0xbfb8aa3b, v22
	v_mul_f32_e32 v15, 0xbfb8aa3b, v23
	v_exp_f32_e32 v12, v12
	v_exp_f32_e32 v13, v13
	v_exp_f32_e32 v14, v14
	v_exp_f32_e32 v15, v15
	v_add_f32_e32 v12, 1.0, v12
	v_add_f32_e32 v13, 1.0, v13
	v_add_f32_e32 v14, 1.0, v14
	v_add_f32_e32 v15, 1.0, v15
	v_rcp_f32_e32 v12, v12
	v_rcp_f32_e32 v13, v13
	v_rcp_f32_e32 v14, v14
	v_rcp_f32_e32 v15, v15
	v_mul_f32_e32 v12, v20, v12
	v_mul_f32_e32 v13, v21, v13
	v_mul_f32_e32 v14, v22, v14
	v_mul_f32_e32 v15, v23, v15
	v_mul_f32_e32 v12, v24, v12
	v_mul_f32_e32 v13, v25, v13
	v_mul_f32_e32 v14, v26, v14
	v_mul_f32_e32 v15, v27, v15
	v_cvt_pk_bf16_f32 v12, v12, v13
	v_cvt_pk_bf16_f32 v13, v14, v15
	global_store_dwordx2 v120, v[12:13], s[22:23]
	v_cmp_eq_u32_e64 s[72:73], 0, v123
	v_cmp_eq_u32_e64 s[74:75], 3, v123
	s_and_b64 s[72:73], s[72:73], s[36:37]
	s_and_b64 s[74:75], s[74:75], s[54:55]
	s_or_b64 vcc, s[72:73], s[74:75]
	v_cndmask_b32_e64 v28, v28, 0, vcc
	v_cndmask_b32_e64 v29, v29, 0, vcc
	v_cndmask_b32_e64 v30, v30, 0, vcc
	v_cndmask_b32_e64 v31, v31, 0, vcc
	v_fmac_f32_e32 v36, v32, v28
	v_fmac_f32_e32 v37, v33, v29
	v_fmac_f32_e32 v38, v34, v30
	v_fmac_f32_e32 v39, v35, v31
	v_mul_f32_e32 v28, 0xbfb8aa3b, v36
	v_mul_f32_e32 v29, 0xbfb8aa3b, v37
	v_mul_f32_e32 v30, 0xbfb8aa3b, v38
	v_mul_f32_e32 v31, 0xbfb8aa3b, v39
	v_exp_f32_e32 v28, v28
	v_exp_f32_e32 v29, v29
	v_exp_f32_e32 v30, v30
	v_exp_f32_e32 v31, v31
	v_add_f32_e32 v28, 1.0, v28
	v_add_f32_e32 v29, 1.0, v29
	v_add_f32_e32 v30, 1.0, v30
	v_add_f32_e32 v31, 1.0, v31
	v_rcp_f32_e32 v28, v28
	v_rcp_f32_e32 v29, v29
	v_rcp_f32_e32 v30, v30
	v_rcp_f32_e32 v31, v31
	v_mul_f32_e32 v28, v36, v28
	v_mul_f32_e32 v29, v37, v29
	v_mul_f32_e32 v30, v38, v30
	v_mul_f32_e32 v31, v39, v31
	v_mul_f32_e32 v28, v40, v28
	v_mul_f32_e32 v29, v41, v29
	v_mul_f32_e32 v30, v42, v30
	v_mul_f32_e32 v31, v43, v31
	v_cvt_pk_bf16_f32 v28, v28, v29
	v_cvt_pk_bf16_f32 v29, v30, v31
	global_store_dwordx2 v122, v[28:29], s[22:23]
	v_cmp_eq_u32_e64 s[72:73], 0, v125
	v_cmp_eq_u32_e64 s[74:75], 3, v125
	s_and_b64 s[72:73], s[72:73], s[36:37]
	s_and_b64 s[74:75], s[74:75], s[54:55]
	s_or_b64 vcc, s[72:73], s[74:75]
	v_cndmask_b32_e64 v44, v44, 0, vcc
	v_cndmask_b32_e64 v45, v45, 0, vcc
	v_cndmask_b32_e64 v46, v46, 0, vcc
	v_cndmask_b32_e64 v47, v47, 0, vcc
	v_fmac_f32_e32 v52, v48, v44
	v_fmac_f32_e32 v53, v49, v45
	v_fmac_f32_e32 v54, v50, v46
	v_fmac_f32_e32 v55, v51, v47
	v_mul_f32_e32 v44, 0xbfb8aa3b, v52
	v_mul_f32_e32 v45, 0xbfb8aa3b, v53
	v_mul_f32_e32 v46, 0xbfb8aa3b, v54
	v_mul_f32_e32 v47, 0xbfb8aa3b, v55
	v_exp_f32_e32 v44, v44
	v_exp_f32_e32 v45, v45
	v_exp_f32_e32 v46, v46
	v_exp_f32_e32 v47, v47
	v_add_f32_e32 v44, 1.0, v44
	v_add_f32_e32 v45, 1.0, v45
	v_add_f32_e32 v46, 1.0, v46
	v_add_f32_e32 v47, 1.0, v47
	v_rcp_f32_e32 v44, v44
	v_rcp_f32_e32 v45, v45
	v_rcp_f32_e32 v46, v46
	v_rcp_f32_e32 v47, v47
	v_mul_f32_e32 v44, v52, v44
	v_mul_f32_e32 v45, v53, v45
	v_mul_f32_e32 v46, v54, v46
	v_mul_f32_e32 v47, v55, v47
	v_mul_f32_e32 v44, v56, v44
	v_mul_f32_e32 v45, v57, v45
	v_mul_f32_e32 v46, v58, v46
	v_mul_f32_e32 v47, v59, v47
	v_cvt_pk_bf16_f32 v44, v44, v45
	v_cvt_pk_bf16_f32 v45, v46, v47
	global_store_dwordx2 v124, v[44:45], s[22:23]
	v_cmp_eq_u32_e64 s[72:73], 0, v127
	v_cmp_eq_u32_e64 s[74:75], 3, v127
	s_and_b64 s[72:73], s[72:73], s[36:37]
	s_and_b64 s[74:75], s[74:75], s[54:55]
	s_or_b64 vcc, s[72:73], s[74:75]
	v_cndmask_b32_e64 v60, v60, 0, vcc
	v_cndmask_b32_e64 v61, v61, 0, vcc
	v_cndmask_b32_e64 v62, v62, 0, vcc
	v_cndmask_b32_e64 v63, v63, 0, vcc
	v_fmac_f32_e32 v68, v64, v60
	v_fmac_f32_e32 v69, v65, v61
	v_fmac_f32_e32 v70, v66, v62
	v_fmac_f32_e32 v71, v67, v63
	v_mul_f32_e32 v60, 0xbfb8aa3b, v68
	v_mul_f32_e32 v61, 0xbfb8aa3b, v69
	v_mul_f32_e32 v62, 0xbfb8aa3b, v70
	v_mul_f32_e32 v63, 0xbfb8aa3b, v71
	v_exp_f32_e32 v60, v60
	v_exp_f32_e32 v61, v61
	v_exp_f32_e32 v62, v62
	v_exp_f32_e32 v63, v63
	v_add_f32_e32 v60, 1.0, v60
	v_add_f32_e32 v61, 1.0, v61
	v_add_f32_e32 v62, 1.0, v62
	v_add_f32_e32 v63, 1.0, v63
	v_rcp_f32_e32 v60, v60
	v_rcp_f32_e32 v61, v61
	v_rcp_f32_e32 v62, v62
	v_rcp_f32_e32 v63, v63
	v_mul_f32_e32 v60, v68, v60
	v_mul_f32_e32 v61, v69, v61
	v_mul_f32_e32 v62, v70, v62
	v_mul_f32_e32 v63, v71, v63
	v_mul_f32_e32 v60, v72, v60
	v_mul_f32_e32 v61, v73, v61
	v_mul_f32_e32 v62, v74, v62
	v_mul_f32_e32 v63, v75, v63
	v_cvt_pk_bf16_f32 v60, v60, v61
	v_cvt_pk_bf16_f32 v61, v62, v63
	global_store_dwordx2 v126, v[60:61], s[22:23]
	v_cmp_eq_u32_e64 s[72:73], 0, v129
	v_cmp_eq_u32_e64 s[74:75], 3, v129
	s_and_b64 s[72:73], s[72:73], s[36:37]
	s_and_b64 s[74:75], s[74:75], s[54:55]
	s_or_b64 vcc, s[72:73], s[74:75]
	v_cndmask_b32_e64 v88, v88, 0, vcc
	v_cndmask_b32_e64 v89, v89, 0, vcc
	v_cndmask_b32_e64 v90, v90, 0, vcc
	v_cndmask_b32_e64 v91, v91, 0, vcc
	v_fmac_f32_e32 v96, v92, v88
	v_fmac_f32_e32 v97, v93, v89
	v_fmac_f32_e32 v98, v94, v90
	v_fmac_f32_e32 v99, v95, v91
	v_mul_f32_e32 v88, 0xbfb8aa3b, v96
	v_mul_f32_e32 v89, 0xbfb8aa3b, v97
	v_mul_f32_e32 v90, 0xbfb8aa3b, v98
	v_mul_f32_e32 v91, 0xbfb8aa3b, v99
	v_exp_f32_e32 v88, v88
	v_exp_f32_e32 v89, v89
; DI float silu(float v) { return v * __builtin_amdgcn_rcpf(1.f + __builtin_amdgcn_exp2f(-1.4426950408889634f * v)); }
; DI void st_bf16x4(bf16_t* p, f32x4 v) { u32x2 w; w.x = cvt_pk_bf16(v[0], v[1]); w.y = cvt_pk_bf16(v[2], v[3]); *(u32x2*)p = w; }
; DI void glu_fix_panel(const Params& p, int l, int pm) {
;     ...
;     for (int it = tid_; it < 4 * (DFF / 4); it += 512) {
;         const int col = (it % (DFF / 4)) * 4, e = it / (DFF / 4);
;         f32x4 nb = (f32x4){0.f, 0.f, 0.f, 0.f}; int tap; int tok;
;         if (e == 0) { tap = 0; tok = 0; if (!(pr == 0 || pr == 1)) nb = *(const f32x4*)(EA + ((size_t)(pm - 1) * 4 + 3) * DFF + col); }
;         else if (e == 1) { tap = 2; tok = 127; nb = *(const f32x4*)(EA + ((size_t)pm * 4 + 2) * DFF + col); }
;         else if (e == 2) { tap = 0; tok = 128; nb = *(const f32x4*)(EA + ((size_t)pm * 4 + 1) * DFF + col); }
;         else { tap = 2; tok = 255; if (!(pr == 0 || pr == 8)) nb = *(const f32x4*)(EA + ((size_t)(pm + 1) * 4 + 0) * DFF + col); }
;         const f32x4 w = *(const f32x4*)(cw + (size_t)tap * DFF + col);
;         const size_t eo = ((size_t)pm * 4 + e) * DFF + col;
;         const f32x4 pp = *(const f32x4*)(EP + eo), uu = *(const f32x4*)(EU + eo);
;         f32x4 g;
; #pragma unroll
;         for (int j = 0; j < 4; ++j) g[j] = silu(pp[j] + w[j] * nb[j]) * uu[j];
;         st_bf16x4(G + ((size_t)pm * BM + tok) * DFF + col, g);
;     }
	v_exp_f32_e32 v90, v90
	v_exp_f32_e32 v91, v91
	v_add_f32_e32 v88, 1.0, v88
	v_add_f32_e32 v89, 1.0, v89
	v_add_f32_e32 v90, 1.0, v90
	v_add_f32_e32 v91, 1.0, v91
	v_rcp_f32_e32 v88, v88
	v_rcp_f32_e32 v89, v89
	v_rcp_f32_e32 v90, v90
	v_rcp_f32_e32 v91, v91
	v_mul_f32_e32 v88, v96, v88
	v_mul_f32_e32 v89, v97, v89
	v_mul_f32_e32 v90, v98, v90
	v_mul_f32_e32 v91, v99, v91
	v_mul_f32_e32 v88, v100, v88
	v_mul_f32_e32 v89, v101, v89
	v_mul_f32_e32 v90, v102, v90
	v_mul_f32_e32 v91, v103, v91
	v_cvt_pk_bf16_f32 v88, v88, v89
	v_cvt_pk_bf16_f32 v89, v90, v91
	global_store_dwordx2 v128, v[88:89], s[22:23]
	v_cmp_eq_u32_e64 s[72:73], 0, v131
	v_cmp_eq_u32_e64 s[74:75], 3, v131
	s_and_b64 s[72:73], s[72:73], s[36:37]
	s_and_b64 s[74:75], s[74:75], s[54:55]
	s_or_b64 vcc, s[72:73], s[74:75]
	v_cndmask_b32_e64 v104, v104, 0, vcc
	v_cndmask_b32_e64 v105, v105, 0, vcc
	v_cndmask_b32_e64 v106, v106, 0, vcc
	v_cndmask_b32_e64 v107, v107, 0, vcc
	v_fmac_f32_e32 v112, v108, v104
	v_fmac_f32_e32 v113, v109, v105
	v_fmac_f32_e32 v114, v110, v106
	v_fmac_f32_e32 v115, v111, v107
	v_mul_f32_e32 v104, 0xbfb8aa3b, v112
	v_mul_f32_e32 v105, 0xbfb8aa3b, v113
	v_mul_f32_e32 v106, 0xbfb8aa3b, v114
	v_mul_f32_e32 v107, 0xbfb8aa3b, v115
	v_exp_f32_e32 v104, v104
	v_exp_f32_e32 v105, v105
	v_exp_f32_e32 v106, v106
	v_exp_f32_e32 v107, v107
	v_add_f32_e32 v104, 1.0, v104
	v_add_f32_e32 v105, 1.0, v105
	v_add_f32_e32 v106, 1.0, v106
	v_add_f32_e32 v107, 1.0, v107
	v_rcp_f32_e32 v104, v104
	v_rcp_f32_e32 v105, v105
	v_rcp_f32_e32 v106, v106
	v_rcp_f32_e32 v107, v107
	v_mul_f32_e32 v104, v112, v104
	v_mul_f32_e32 v105, v113, v105
	v_mul_f32_e32 v106, v114, v106
	v_mul_f32_e32 v107, v115, v107
	v_mul_f32_e32 v104, v116, v104
	v_mul_f32_e32 v105, v117, v105
	v_mul_f32_e32 v106, v118, v106
	v_mul_f32_e32 v107, v119, v107
	v_cvt_pk_bf16_f32 v104, v104, v105
	v_cvt_pk_bf16_f32 v105, v106, v107
	global_store_dwordx2 v130, v[104:105], s[22:23]
	v_add_u32_e32 v140, 0xc00, v202
	v_mul_hi_u32 v121, v140, s27
	v_mul_u32_u24_e32 v142, 0x580, v121
	v_sub_u32_e32 v141, v140, v142
	v_mul_u32_u24_e32 v142, 0x5800, v121
	v_lshl_add_u32 v145, v141, 4, v142
	v_and_b32_e32 v144, 1, v121
	v_mul_u32_u24_e32 v143, 0xb000, v144
	v_add_u32_e32 v146, v143, v145
	v_add_u32_e32 v148, 0x5800, v145
	v_lshl_add_u32 v147, v141, 4, v143
	v_lshrrev_b32_e32 v149, 1, v121
	v_mul_u32_u24_e32 v149, 0x160000, v149
	v_mul_u32_u24_e32 v150, 0x15d400, v144
	v_lshlrev_b32_e32 v142, 3, v141
	v_add3_u32 v120, v149, v150, v142
	v_cmp_eq_u32_e64 s[72:73], 0, v121
	v_cmp_eq_u32_e64 s[74:75], 3, v121
	s_and_b64 s[72:73], s[72:73], s[36:37]
	s_and_b64 s[74:75], s[74:75], s[54:55]
	s_or_b64 vcc, s[72:73], s[74:75]
	v_cndmask_b32_e32 v146, v146, v148, vcc
	global_load_dwordx4 v[12:15], v146, s[6:7]
	global_load_dwordx4 v[16:19], v147, s[38:39]
	global_load_dwordx4 v[20:23], v145, s[2:3]
	global_load_dwordx4 v[24:27], v145, s[4:5]
	v_add_u32_e32 v140, 0xe00, v202
	v_mul_hi_u32 v123, v140, s27
	v_mul_u32_u24_e32 v142, 0x580, v123
	v_sub_u32_e32 v141, v140, v142
	v_mul_u32_u24_e32 v142, 0x5800, v123
	v_lshl_add_u32 v145, v141, 4, v142
	v_and_b32_e32 v144, 1, v123
	v_mul_u32_u24_e32 v143, 0xb000, v144
	v_add_u32_e32 v146, v143, v145
	v_add_u32_e32 v148, 0x5800, v145
	v_lshl_add_u32 v147, v141, 4, v143
	v_lshrrev_b32_e32 v149, 1, v123
	v_mul_u32_u24_e32 v149, 0x160000, v149
	v_mul_u32_u24_e32 v150, 0x15d400, v144
	v_lshlrev_b32_e32 v142, 3, v141
	v_add3_u32 v122, v149, v150, v142
	v_cmp_eq_u32_e64 s[72:73], 0, v123
	v_cmp_eq_u32_e64 s[74:75], 3, v123
	s_and_b64 s[72:73], s[72:73], s[36:37]
	s_and_b64 s[74:75], s[74:75], s[54:55]
	s_or_b64 vcc, s[72:73], s[74:75]
	v_cndmask_b32_e32 v146, v146, v148, vcc
	global_load_dwordx4 v[28:31], v146, s[6:7]
	global_load_dwordx4 v[32:35], v147, s[38:39]
	global_load_dwordx4 v[36:39], v145, s[2:3]
	global_load_dwordx4 v[40:43], v145, s[4:5]
	v_add_u32_e32 v140, 0x1000, v202
	v_mul_hi_u32 v125, v140, s27
	v_mul_u32_u24_e32 v142, 0x580, v125
	v_sub_u32_e32 v141, v140, v142
	v_mul_u32_u24_e32 v142, 0x5800, v125
	v_lshl_add_u32 v145, v141, 4, v142
	v_and_b32_e32 v144, 1, v125
	v_mul_u32_u24_e32 v143, 0xb000, v144
	v_add_u32_e32 v146, v143, v145
	v_add_u32_e32 v148, 0x5800, v145
	v_lshl_add_u32 v147, v141, 4, v143
	v_lshrrev_b32_e32 v149, 1, v125
	v_mul_u32_u24_e32 v149, 0x160000, v149
	v_mul_u32_u24_e32 v150, 0x15d400, v144
	v_lshlrev_b32_e32 v142, 3, v141
	v_add3_u32 v124, v149, v150, v142
	v_cmp_eq_u32_e64 s[72:73], 0, v125
	v_cmp_eq_u32_e64 s[74:75], 3, v125
	s_and_b64 s[72:73], s[72:73], s[36:37]
	s_and_b64 s[74:75], s[74:75], s[54:55]
	s_or_b64 vcc, s[72:73], s[74:75]
	v_cndmask_b32_e32 v146, v146, v148, vcc
	global_load_dwordx4 v[44:47], v146, s[6:7]
	global_load_dwordx4 v[48:51], v147, s[38:39]
	global_load_dwordx4 v[52:55], v145, s[2:3]
	global_load_dwordx4 v[56:59], v145, s[4:5]
	v_add_u32_e32 v140, 0x1200, v202
	v_mul_hi_u32 v127, v140, s27
	v_mul_u32_u24_e32 v142, 0x580, v127
	v_sub_u32_e32 v141, v140, v142
	v_mul_u32_u24_e32 v142, 0x5800, v127
	v_lshl_add_u32 v145, v141, 4, v142
	v_and_b32_e32 v144, 1, v127
	v_mul_u32_u24_e32 v143, 0xb000, v144
	v_add_u32_e32 v146, v143, v145
	v_add_u32_e32 v148, 0x5800, v145
	v_lshl_add_u32 v147, v141, 4, v143
	v_lshrrev_b32_e32 v149, 1, v127
	v_mul_u32_u24_e32 v149, 0x160000, v149
	v_mul_u32_u24_e32 v150, 0x15d400, v144
	v_lshlrev_b32_e32 v142, 3, v141
	v_add3_u32 v126, v149, v150, v142
	v_cmp_eq_u32_e64 s[72:73], 0, v127
	v_cmp_eq_u32_e64 s[74:75], 3, v127
	s_and_b64 s[72:73], s[72:73], s[36:37]
	s_and_b64 s[74:75], s[74:75], s[54:55]
	s_or_b64 vcc, s[72:73], s[74:75]
	v_cndmask_b32_e32 v146, v146, v148, vcc
	global_load_dwordx4 v[60:63], v146, s[6:7]
	global_load_dwordx4 v[64:67], v147, s[38:39]
	global_load_dwordx4 v[68:71], v145, s[2:3]
	global_load_dwordx4 v[72:75], v145, s[4:5]
	v_add_u32_e32 v140, 0x1400, v202
	v_mul_hi_u32 v129, v140, s27
	v_mul_u32_u24_e32 v142, 0x580, v129
	v_sub_u32_e32 v141, v140, v142
	v_mul_u32_u24_e32 v142, 0x5800, v129
	v_lshl_add_u32 v145, v141, 4, v142
	v_and_b32_e32 v144, 1, v129
	v_mul_u32_u24_e32 v143, 0xb000, v144
	v_add_u32_e32 v146, v143, v145
	v_add_u32_e32 v148, 0x5800, v145
	v_lshl_add_u32 v147, v141, 4, v143
	v_lshrrev_b32_e32 v149, 1, v129
	v_mul_u32_u24_e32 v149, 0x160000, v149
	v_mul_u32_u24_e32 v150, 0x15d400, v144
	v_lshlrev_b32_e32 v142, 3, v141
	v_add3_u32 v128, v149, v150, v142
	v_cmp_eq_u32_e64 s[72:73], 0, v129
	v_cmp_eq_u32_e64 s[74:75], 3, v129
	s_and_b64 s[72:73], s[72:73], s[36:37]
	s_and_b64 s[74:75], s[74:75], s[54:55]
	s_or_b64 vcc, s[72:73], s[74:75]
	v_cndmask_b32_e32 v146, v146, v148, vcc
	global_load_dwordx4 v[88:91], v146, s[6:7]
	global_load_dwordx4 v[92:95], v147, s[38:39]
	global_load_dwordx4 v[96:99], v145, s[2:3]
	global_load_dwordx4 v[100:103], v145, s[4:5]
	s_waitcnt vmcnt(0)
; DI float silu(float v) { return v * __builtin_amdgcn_rcpf(1.f + __builtin_amdgcn_exp2f(-1.4426950408889634f * v)); }
; DI void st_bf16x4(bf16_t* p, f32x4 v) { u32x2 w; w.x = cvt_pk_bf16(v[0], v[1]); w.y = cvt_pk_bf16(v[2], v[3]); *(u32x2*)p = w; }
; DI void glu_fix_panel(const Params& p, int l, int pm) {
;     ...
;         f32x4 nb = (f32x4){0.f, 0.f, 0.f, 0.f}; int tap; int tok;
;         if (e == 0) { tap = 0; tok = 0; if (!(pr == 0 || pr == 1)) nb = *(const f32x4*)(EA + ((size_t)(pm - 1) * 4 + 3) * DFF + col); }
;         else if (e == 1) { tap = 2; tok = 127; nb = *(const f32x4*)(EA + ((size_t)pm * 4 + 2) * DFF + col); }
;         else if (e == 2) { tap = 0; tok = 128; nb = *(const f32x4*)(EA + ((size_t)pm * 4 + 1) * DFF + col); }
;         else { tap = 2; tok = 255; if (!(pr == 0 || pr == 8)) nb = *(const f32x4*)(EA + ((size_t)(pm + 1) * 4 + 0) * DFF + col); }
;         const f32x4 w = *(const f32x4*)(cw + (size_t)tap * DFF + col);
;         const size_t eo = ((size_t)pm * 4 + e) * DFF + col;
;         const f32x4 pp = *(const f32x4*)(EP + eo), uu = *(const f32x4*)(EU + eo);
;         f32x4 g;
; #pragma unroll
;         for (int j = 0; j < 4; ++j) g[j] = silu(pp[j] + w[j] * nb[j]) * uu[j];
;         st_bf16x4(G + ((size_t)pm * BM + tok) * DFF + col, g);
	v_cmp_eq_u32_e64 s[72:73], 0, v121
	v_cmp_eq_u32_e64 s[74:75], 3, v121
	s_and_b64 s[72:73], s[72:73], s[36:37]
	s_and_b64 s[74:75], s[74:75], s[54:55]
	s_or_b64 vcc, s[72:73], s[74:75]
	v_cndmask_b32_e64 v12, v12, 0, vcc
	v_cndmask_b32_e64 v13, v13, 0, vcc
	v_cndmask_b32_e64 v14, v14, 0, vcc
	v_cndmask_b32_e64 v15, v15, 0, vcc
	v_fmac_f32_e32 v20, v16, v12
	v_fmac_f32_e32 v21, v17, v13
	v_fmac_f32_e32 v22, v18, v14
	v_fmac_f32_e32 v23, v19, v15
	v_mul_f32_e32 v12, 0xbfb8aa3b, v20
	v_mul_f32_e32 v13, 0xbfb8aa3b, v21
	v_mul_f32_e32 v14, 0xbfb8aa3b, v22
	v_mul_f32_e32 v15, 0xbfb8aa3b, v23
	v_exp_f32_e32 v12, v12
	v_exp_f32_e32 v13, v13
	v_exp_f32_e32 v14, v14
	v_exp_f32_e32 v15, v15
	v_add_f32_e32 v12, 1.0, v12
	v_add_f32_e32 v13, 1.0, v13
	v_add_f32_e32 v14, 1.0, v14
	v_add_f32_e32 v15, 1.0, v15
	v_rcp_f32_e32 v12, v12
	v_rcp_f32_e32 v13, v13
	v_rcp_f32_e32 v14, v14
	v_rcp_f32_e32 v15, v15
	v_mul_f32_e32 v12, v20, v12
	v_mul_f32_e32 v13, v21, v13
	v_mul_f32_e32 v14, v22, v14
	v_mul_f32_e32 v15, v23, v15
	v_mul_f32_e32 v12, v24, v12
	v_mul_f32_e32 v13, v25, v13
	v_mul_f32_e32 v14, v26, v14
	v_mul_f32_e32 v15, v27, v15
	v_cvt_pk_bf16_f32 v12, v12, v13
	v_cvt_pk_bf16_f32 v13, v14, v15
	global_store_dwordx2 v120, v[12:13], s[22:23]
	v_cmp_eq_u32_e64 s[72:73], 0, v123
	v_cmp_eq_u32_e64 s[74:75], 3, v123
	s_and_b64 s[72:73], s[72:73], s[36:37]
	s_and_b64 s[74:75], s[74:75], s[54:55]
	s_or_b64 vcc, s[72:73], s[74:75]
	v_cndmask_b32_e64 v28, v28, 0, vcc
	v_cndmask_b32_e64 v29, v29, 0, vcc
	v_cndmask_b32_e64 v30, v30, 0, vcc
	v_cndmask_b32_e64 v31, v31, 0, vcc
	v_fmac_f32_e32 v36, v32, v28
	v_fmac_f32_e32 v37, v33, v29
	v_fmac_f32_e32 v38, v34, v30
	v_fmac_f32_e32 v39, v35, v31
	v_mul_f32_e32 v28, 0xbfb8aa3b, v36
	v_mul_f32_e32 v29, 0xbfb8aa3b, v37
	v_mul_f32_e32 v30, 0xbfb8aa3b, v38
	v_mul_f32_e32 v31, 0xbfb8aa3b, v39
	v_exp_f32_e32 v28, v28
	v_exp_f32_e32 v29, v29
	v_exp_f32_e32 v30, v30
	v_exp_f32_e32 v31, v31
	v_add_f32_e32 v28, 1.0, v28
	v_add_f32_e32 v29, 1.0, v29
	v_add_f32_e32 v30, 1.0, v30
	v_add_f32_e32 v31, 1.0, v31
	v_rcp_f32_e32 v28, v28
	v_rcp_f32_e32 v29, v29
	v_rcp_f32_e32 v30, v30
	v_rcp_f32_e32 v31, v31
	v_mul_f32_e32 v28, v36, v28
	v_mul_f32_e32 v29, v37, v29
	v_mul_f32_e32 v30, v38, v30
	v_mul_f32_e32 v31, v39, v31
	v_mul_f32_e32 v28, v40, v28
	v_mul_f32_e32 v29, v41, v29
	v_mul_f32_e32 v30, v42, v30
	v_mul_f32_e32 v31, v43, v31
	v_cvt_pk_bf16_f32 v28, v28, v29
	v_cvt_pk_bf16_f32 v29, v30, v31
	global_store_dwordx2 v122, v[28:29], s[22:23]
	v_cmp_eq_u32_e64 s[72:73], 0, v125
	v_cmp_eq_u32_e64 s[74:75], 3, v125
	s_and_b64 s[72:73], s[72:73], s[36:37]
	s_and_b64 s[74:75], s[74:75], s[54:55]
	s_or_b64 vcc, s[72:73], s[74:75]
	v_cndmask_b32_e64 v44, v44, 0, vcc
	v_cndmask_b32_e64 v45, v45, 0, vcc
	v_cndmask_b32_e64 v46, v46, 0, vcc
	v_cndmask_b32_e64 v47, v47, 0, vcc
	v_fmac_f32_e32 v52, v48, v44
	v_fmac_f32_e32 v53, v49, v45
	v_fmac_f32_e32 v54, v50, v46
	v_fmac_f32_e32 v55, v51, v47
	v_mul_f32_e32 v44, 0xbfb8aa3b, v52
	v_mul_f32_e32 v45, 0xbfb8aa3b, v53
	v_mul_f32_e32 v46, 0xbfb8aa3b, v54
	v_mul_f32_e32 v47, 0xbfb8aa3b, v55
	v_exp_f32_e32 v44, v44
	v_exp_f32_e32 v45, v45
	v_exp_f32_e32 v46, v46
	v_exp_f32_e32 v47, v47
	v_add_f32_e32 v44, 1.0, v44
	v_add_f32_e32 v45, 1.0, v45
	v_add_f32_e32 v46, 1.0, v46
	v_add_f32_e32 v47, 1.0, v47
	v_rcp_f32_e32 v44, v44
	v_rcp_f32_e32 v45, v45
	v_rcp_f32_e32 v46, v46
	v_rcp_f32_e32 v47, v47
	v_mul_f32_e32 v44, v52, v44
	v_mul_f32_e32 v45, v53, v45
	v_mul_f32_e32 v46, v54, v46
	v_mul_f32_e32 v47, v55, v47
	v_mul_f32_e32 v44, v56, v44
	v_mul_f32_e32 v45, v57, v45
	v_mul_f32_e32 v46, v58, v46
	v_mul_f32_e32 v47, v59, v47
	v_cvt_pk_bf16_f32 v44, v44, v45
	v_cvt_pk_bf16_f32 v45, v46, v47
	global_store_dwordx2 v124, v[44:45], s[22:23]
	v_cmp_eq_u32_e64 s[72:73], 0, v127
	v_cmp_eq_u32_e64 s[74:75], 3, v127
	s_and_b64 s[72:73], s[72:73], s[36:37]
	s_and_b64 s[74:75], s[74:75], s[54:55]
	s_or_b64 vcc, s[72:73], s[74:75]
	v_cndmask_b32_e64 v60, v60, 0, vcc
	v_cndmask_b32_e64 v61, v61, 0, vcc
	v_cndmask_b32_e64 v62, v62, 0, vcc
	v_cndmask_b32_e64 v63, v63, 0, vcc
	v_fmac_f32_e32 v68, v64, v60
	v_fmac_f32_e32 v69, v65, v61
	v_fmac_f32_e32 v70, v66, v62
	v_fmac_f32_e32 v71, v67, v63
	v_mul_f32_e32 v60, 0xbfb8aa3b, v68
	v_mul_f32_e32 v61, 0xbfb8aa3b, v69
	v_mul_f32_e32 v62, 0xbfb8aa3b, v70
	v_mul_f32_e32 v63, 0xbfb8aa3b, v71
	v_exp_f32_e32 v60, v60
	v_exp_f32_e32 v61, v61
	v_exp_f32_e32 v62, v62
	v_exp_f32_e32 v63, v63
	v_add_f32_e32 v60, 1.0, v60
	v_add_f32_e32 v61, 1.0, v61
	v_add_f32_e32 v62, 1.0, v62
	v_add_f32_e32 v63, 1.0, v63
	v_rcp_f32_e32 v60, v60
	v_rcp_f32_e32 v61, v61
	v_rcp_f32_e32 v62, v62
	v_rcp_f32_e32 v63, v63
	v_mul_f32_e32 v60, v68, v60
	v_mul_f32_e32 v61, v69, v61
	v_mul_f32_e32 v62, v70, v62
	v_mul_f32_e32 v63, v71, v63
	v_mul_f32_e32 v60, v72, v60
	v_mul_f32_e32 v61, v73, v61
	v_mul_f32_e32 v62, v74, v62
	v_mul_f32_e32 v63, v75, v63
	v_cvt_pk_bf16_f32 v60, v60, v61
	v_cvt_pk_bf16_f32 v61, v62, v63
	global_store_dwordx2 v126, v[60:61], s[22:23]
	v_cmp_eq_u32_e64 s[72:73], 0, v129
	v_cmp_eq_u32_e64 s[74:75], 3, v129
	s_and_b64 s[72:73], s[72:73], s[36:37]
	s_and_b64 s[74:75], s[74:75], s[54:55]
	s_or_b64 vcc, s[72:73], s[74:75]
	v_cndmask_b32_e64 v88, v88, 0, vcc
	v_cndmask_b32_e64 v89, v89, 0, vcc
	v_cndmask_b32_e64 v90, v90, 0, vcc
	v_cndmask_b32_e64 v91, v91, 0, vcc
	v_fmac_f32_e32 v96, v92, v88
	v_fmac_f32_e32 v97, v93, v89
	v_fmac_f32_e32 v98, v94, v90
	v_fmac_f32_e32 v99, v95, v91
	v_mul_f32_e32 v88, 0xbfb8aa3b, v96
	v_mul_f32_e32 v89, 0xbfb8aa3b, v97
	v_mul_f32_e32 v90, 0xbfb8aa3b, v98
	v_mul_f32_e32 v91, 0xbfb8aa3b, v99
	v_exp_f32_e32 v88, v88
	v_exp_f32_e32 v89, v89
	v_exp_f32_e32 v90, v90
	v_exp_f32_e32 v91, v91
	v_add_f32_e32 v88, 1.0, v88
	v_add_f32_e32 v89, 1.0, v89
	v_add_f32_e32 v90, 1.0, v90
	v_add_f32_e32 v91, 1.0, v91
	v_rcp_f32_e32 v88, v88
	v_rcp_f32_e32 v89, v89
	v_rcp_f32_e32 v90, v90
	v_rcp_f32_e32 v91, v91
	v_mul_f32_e32 v88, v96, v88
	v_mul_f32_e32 v89, v97, v89
	v_mul_f32_e32 v90, v98, v90
	v_mul_f32_e32 v91, v99, v91
	v_mul_f32_e32 v88, v100, v88
	v_mul_f32_e32 v89, v101, v89
	v_mul_f32_e32 v90, v102, v90
	v_mul_f32_e32 v91, v103, v91
	v_cvt_pk_bf16_f32 v88, v88, v89
	v_cvt_pk_bf16_f32 v89, v90, v91
	global_store_dwordx2 v128, v[88:89], s[22:23]

; DI int otid() { int t = threadIdx.x; asm volatile("" : "+v"(t)); return t; }
; DI void glu_fix_panel(const Params& p, int l, int pm) {
;     unsigned char* ws = p.ws;
;     bf16_t* G = (bf16_t*)(ws + WS_G);
;     const float* EA = (const float*)(ws + WS_EDGE); const float* EP = EA + (size_t)36 * 4 * DFF; const float* EU = EP + (size_t)36 * 4 * DFF;
;     const float* cw = p.in[17] + (size_t)l * 3 * DFF;
;     const int tid_ = otid();
;     const int pr = pm % 9;
;     for (int it = tid_; it < 4 * (DFF / 4); it += 512) {
;         const int col = (it % (DFF / 4)) * 4, e = it / (DFF / 4);
;         f32x4 nb = (f32x4){0.f, 0.f, 0.f, 0.f}; int tap; int tok;
;         if (e == 0) { tap = 0; tok = 0; if (!(pr == 0 || pr == 1)) nb = *(const f32x4*)(EA + ((size_t)(pm - 1) * 4 + 3) * DFF + col); }
;         else if (e == 1) { tap = 2; tok = 127; nb = *(const f32x4*)(EA + ((size_t)pm * 4 + 2) * DFF + col); }
;         else if (e == 2) { tap = 0; tok = 128; nb = *(const f32x4*)(EA + ((size_t)pm * 4 + 1) * DFF + col); }
;         else { tap = 2; tok = 255; if (!(pr == 0 || pr == 8)) nb = *(const f32x4*)(EA + ((size_t)(pm + 1) * 4 + 0) * DFF + col); }
;         const f32x4 w = *(const f32x4*)(cw + (size_t)tap * DFF + col);
;         const size_t eo = ((size_t)pm * 4 + e) * DFF + col;
;         const f32x4 pp = *(const f32x4*)(EP + eo), uu = *(const f32x4*)(EU + eo);
.LBB0_1630:
	s_andn2_b64 vcc, exec, s[10:11]
	s_cbranch_vccnz .LBB0_1651
	s_mov_b32 s9, s8
	s_mul_i32 s29, s9, 57
	s_lshr_b32 s29, s29, 9
	s_mul_i32 s29, s29, 9
	s_sub_u32 s11, s9, s29
	s_cmp_lt_u32 s11, 2
	s_cselect_b64 s[36:37], -1, 0
	s_cmp_eq_u32 s11, 0
	s_cselect_b64 s[72:73], -1, 0
	s_cmp_eq_u32 s11, 8
	s_cselect_b64 s[54:55], -1, 0
	s_or_b64 s[54:55], s[54:55], s[72:73]
	s_mul_i32 s29, s9, 0x16000
	s_add_u32 s2, s50, 0x116b8000
	s_addc_u32 s3, s51, 0
	s_add_u32 s2, s2, s29
	s_addc_u32 s3, s3, 0
	s_add_u32 s4, s50, 0x119d0000
	s_addc_u32 s5, s51, 0
	s_add_u32 s4, s4, s29
	s_addc_u32 s5, s5, 0
	s_add_u32 s6, s50, 0x113a0000
	s_addc_u32 s7, s51, 0
	s_add_u32 s6, s6, s29
	s_addc_u32 s7, s7, 0
	s_sub_u32 s6, s6, 0x5800
	s_subb_u32 s7, s7, 0
	s_mul_i32 s29, s9, 0x2c0000
	s_add_u32 s22, s50, 0x1d9a0000
	s_addc_u32 s23, s51, 0
	s_add_u32 s22, s22, s29
	s_addc_u32 s23, s23, 0
	s_mov_b32 s27, 0x2e8ba3
	v_mov_b32_e32 v140, v202
	v_mul_hi_u32 v121, v140, s27
	v_mul_u32_u24_e32 v142, 0x580, v121
	v_sub_u32_e32 v141, v140, v142
	v_mul_u32_u24_e32 v142, 0x5800, v121
	v_lshl_add_u32 v145, v141, 4, v142
	v_and_b32_e32 v144, 1, v121
	v_mul_u32_u24_e32 v143, 0xb000, v144
	v_add_u32_e32 v146, v143, v145
	v_add_u32_e32 v148, 0x5800, v145
	v_lshl_add_u32 v147, v141, 4, v143
	v_lshrrev_b32_e32 v149, 1, v121
	v_mul_u32_u24_e32 v149, 0x160000, v149
	v_mul_u32_u24_e32 v150, 0x15d400, v144
	v_lshlrev_b32_e32 v142, 3, v141
	v_add3_u32 v120, v149, v150, v142
	v_cmp_eq_u32_e64 s[72:73], 0, v121
	v_cmp_eq_u32_e64 s[74:75], 3, v121
	s_and_b64 s[72:73], s[72:73], s[36:37]
	s_and_b64 s[74:75], s[74:75], s[54:55]
	s_or_b64 vcc, s[72:73], s[74:75]
	v_cndmask_b32_e32 v146, v146, v148, vcc
	global_load_dwordx4 v[12:15], v146, s[6:7]
	global_load_dwordx4 v[16:19], v147, s[38:39]
	global_load_dwordx4 v[20:23], v145, s[2:3]
	global_load_dwordx4 v[24:27], v145, s[4:5]
	v_add_u32_e32 v140, 0x200, v202
	v_mul_hi_u32 v123, v140, s27
	v_mul_u32_u24_e32 v142, 0x580, v123
	v_sub_u32_e32 v141, v140, v142
	v_mul_u32_u24_e32 v142, 0x5800, v123
	v_lshl_add_u32 v145, v141, 4, v142
	v_and_b32_e32 v144, 1, v123
	v_mul_u32_u24_e32 v143, 0xb000, v144
	v_add_u32_e32 v146, v143, v145
	v_add_u32_e32 v148, 0x5800, v145
	v_lshl_add_u32 v147, v141, 4, v143
	v_lshrrev_b32_e32 v149, 1, v123
	v_mul_u32_u24_e32 v149, 0x160000, v149
	v_mul_u32_u24_e32 v150, 0x15d400, v144
	v_lshlrev_b32_e32 v142, 3, v141
	v_add3_u32 v122, v149, v150, v142
	v_cmp_eq_u32_e64 s[72:73], 0, v123
	v_cmp_eq_u32_e64 s[74:75], 3, v123
	s_and_b64 s[72:73], s[72:73], s[36:37]
	s_and_b64 s[74:75], s[74:75], s[54:55]
	s_or_b64 vcc, s[72:73], s[74:75]
	v_cndmask_b32_e32 v146, v146, v148, vcc
	global_load_dwordx4 v[28:31], v146, s[6:7]
	global_load_dwordx4 v[32:35], v147, s[38:39]
	global_load_dwordx4 v[36:39], v145, s[2:3]
	global_load_dwordx4 v[40:43], v145, s[4:5]
	v_add_u32_e32 v140, 0x400, v202
	v_mul_hi_u32 v125, v140, s27
	v_mul_u32_u24_e32 v142, 0x580, v125
	v_sub_u32_e32 v141, v140, v142
	v_mul_u32_u24_e32 v142, 0x5800, v125
	v_lshl_add_u32 v145, v141, 4, v142
	v_and_b32_e32 v144, 1, v125
	v_mul_u32_u24_e32 v143, 0xb000, v144
	v_add_u32_e32 v146, v143, v145
	v_add_u32_e32 v148, 0x5800, v145
	v_lshl_add_u32 v147, v141, 4, v143
	v_lshrrev_b32_e32 v149, 1, v125
	v_mul_u32_u24_e32 v149, 0x160000, v149
	v_mul_u32_u24_e32 v150, 0x15d400, v144
	v_lshlrev_b32_e32 v142, 3, v141
	v_add3_u32 v124, v149, v150, v142
	v_cmp_eq_u32_e64 s[72:73], 0, v125
	v_cmp_eq_u32_e64 s[74:75], 3, v125
	s_and_b64 s[72:73], s[72:73], s[36:37]
	s_and_b64 s[74:75], s[74:75], s[54:55]
	s_or_b64 vcc, s[72:73], s[74:75]
	v_cndmask_b32_e32 v146, v146, v148, vcc
	global_load_dwordx4 v[44:47], v146, s[6:7]
	global_load_dwordx4 v[48:51], v147, s[38:39]
	global_load_dwordx4 v[52:55], v145, s[2:3]
	global_load_dwordx4 v[56:59], v145, s[4:5]
	v_add_u32_e32 v140, 0x600, v202
	v_mul_hi_u32 v127, v140, s27
	v_mul_u32_u24_e32 v142, 0x580, v127
	v_sub_u32_e32 v141, v140, v142
	v_mul_u32_u24_e32 v142, 0x5800, v127
	v_lshl_add_u32 v145, v141, 4, v142
	v_and_b32_e32 v144, 1, v127
	v_mul_u32_u24_e32 v143, 0xb000, v144
	v_add_u32_e32 v146, v143, v145
	v_add_u32_e32 v148, 0x5800, v145
	v_lshl_add_u32 v147, v141, 4, v143
	v_lshrrev_b32_e32 v149, 1, v127
	v_mul_u32_u24_e32 v149, 0x160000, v149
	v_mul_u32_u24_e32 v150, 0x15d400, v144
	v_lshlrev_b32_e32 v142, 3, v141
	v_add3_u32 v126, v149, v150, v142
	v_cmp_eq_u32_e64 s[72:73], 0, v127
	v_cmp_eq_u32_e64 s[74:75], 3, v127
	s_and_b64 s[72:73], s[72:73], s[36:37]
	s_and_b64 s[74:75], s[74:75], s[54:55]
	s_or_b64 vcc, s[72:73], s[74:75]
	v_cndmask_b32_e32 v146, v146, v148, vcc
	global_load_dwordx4 v[60:63], v146, s[6:7]
	global_load_dwordx4 v[64:67], v147, s[38:39]
	global_load_dwordx4 v[68:71], v145, s[2:3]
	global_load_dwordx4 v[72:75], v145, s[4:5]
	v_add_u32_e32 v140, 0x800, v202
	v_mul_hi_u32 v129, v140, s27
	v_mul_u32_u24_e32 v142, 0x580, v129
	v_sub_u32_e32 v141, v140, v142
	v_mul_u32_u24_e32 v142, 0x5800, v129
	v_lshl_add_u32 v145, v141, 4, v142
	v_and_b32_e32 v144, 1, v129
	v_mul_u32_u24_e32 v143, 0xb000, v144
	v_add_u32_e32 v146, v143, v145
	v_add_u32_e32 v148, 0x5800, v145
	v_lshl_add_u32 v147, v141, 4, v143
	v_lshrrev_b32_e32 v149, 1, v129
	v_mul_u32_u24_e32 v149, 0x160000, v149
	v_mul_u32_u24_e32 v150, 0x15d400, v144
	v_lshlrev_b32_e32 v142, 3, v141
	v_add3_u32 v128, v149, v150, v142
	v_cmp_eq_u32_e64 s[72:73], 0, v129
	v_cmp_eq_u32_e64 s[74:75], 3, v129
	s_and_b64 s[72:73], s[72:73], s[36:37]
	s_and_b64 s[74:75], s[74:75], s[54:55]
	s_or_b64 vcc, s[72:73], s[74:75]
	v_cndmask_b32_e32 v146, v146, v148, vcc
	global_load_dwordx4 v[88:91], v146, s[6:7]
	global_load_dwordx4 v[92:95], v147, s[38:39]
	global_load_dwordx4 v[96:99], v145, s[2:3]
	global_load_dwordx4 v[100:103], v145, s[4:5]
	v_add_u32_e32 v140, 0xa00, v202
	v_mul_hi_u32 v131, v140, s27
	v_mul_u32_u24_e32 v142, 0x580, v131
	v_sub_u32_e32 v141, v140, v142
	v_mul_u32_u24_e32 v142, 0x5800, v131
	v_lshl_add_u32 v145, v141, 4, v142
	v_and_b32_e32 v144, 1, v131
	v_mul_u32_u24_e32 v143, 0xb000, v144
	v_add_u32_e32 v146, v143, v145
	v_add_u32_e32 v148, 0x5800, v145
	v_lshl_add_u32 v147, v141, 4, v143
	v_lshrrev_b32_e32 v149, 1, v131
	v_mul_u32_u24_e32 v149, 0x160000, v149
	v_mul_u32_u24_e32 v150, 0x15d400, v144
	v_lshlrev_b32_e32 v142, 3, v141
	v_add3_u32 v130, v149, v150, v142
	v_cmp_eq_u32_e64 s[72:73], 0, v131
	v_cmp_eq_u32_e64 s[74:75], 3, v131
	s_and_b64 s[72:73], s[72:73], s[36:37]
	s_and_b64 s[74:75], s[74:75], s[54:55]
	s_or_b64 vcc, s[72:73], s[74:75]
	v_cndmask_b32_e32 v146, v146, v148, vcc
	global_load_dwordx4 v[104:107], v146, s[6:7]
	global_load_dwordx4 v[108:111], v147, s[38:39]
	global_load_dwordx4 v[112:115], v145, s[2:3]
	global_load_dwordx4 v[116:119], v145, s[4:5]
	s_waitcnt vmcnt(0)
; DI float silu(float v) { return v * __builtin_amdgcn_rcpf(1.f + __builtin_amdgcn_exp2f(-1.4426950408889634f * v)); }
; DI void st_bf16x4(bf16_t* p, f32x4 v) { u32x2 w; w.x = cvt_pk_bf16(v[0], v[1]); w.y = cvt_pk_bf16(v[2], v[3]); *(u32x2*)p = w; }
; DI void glu_fix_panel(const Params& p, int l, int pm) {
;     ...
;         f32x4 nb = (f32x4){0.f, 0.f, 0.f, 0.f}; int tap; int tok;
;         if (e == 0) { tap = 0; tok = 0; if (!(pr == 0 || pr == 1)) nb = *(const f32x4*)(EA + ((size_t)(pm - 1) * 4 + 3) * DFF + col); }
;         else if (e == 1) { tap = 2; tok = 127; nb = *(const f32x4*)(EA + ((size_t)pm * 4 + 2) * DFF + col); }
;         else if (e == 2) { tap = 0; tok = 128; nb = *(const f32x4*)(EA + ((size_t)pm * 4 + 1) * DFF + col); }
;         else { tap = 2; tok = 255; if (!(pr == 0 || pr == 8)) nb = *(const f32x4*)(EA + ((size_t)(pm + 1) * 4 + 0) * DFF + col); }
;         const f32x4 w = *(const f32x4*)(cw + (size_t)tap * DFF + col);
;         const size_t eo = ((size_t)pm * 4 + e) * DFF + col;
;         const f32x4 pp = *(const f32x4*)(EP + eo), uu = *(const f32x4*)(EU + eo);
;         f32x4 g;
; #pragma unroll
;         for (int j = 0; j < 4; ++j) g[j] = silu(pp[j] + w[j] * nb[j]) * uu[j];
;         st_bf16x4(G + ((size_t)pm * BM + tok) * DFF + col, g);
	v_cmp_eq_u32_e64 s[72:73], 0, v121
	v_cmp_eq_u32_e64 s[74:75], 3, v121
	s_and_b64 s[72:73], s[72:73], s[36:37]
	s_and_b64 s[74:75], s[74:75], s[54:55]
	s_or_b64 vcc, s[72:73], s[74:75]
	v_cndmask_b32_e64 v12, v12, 0, vcc
	v_cndmask_b32_e64 v13, v13, 0, vcc
	v_cndmask_b32_e64 v14, v14, 0, vcc
	v_cndmask_b32_e64 v15, v15, 0, vcc
	v_fmac_f32_e32 v20, v16, v12
	v_fmac_f32_e32 v21, v17, v13
	v_fmac_f32_e32 v22, v18, v14
	v_fmac_f32_e32 v23, v19, v15
	v_mul_f32_e32 v12, 0xbfb8aa3b, v20
	v_mul_f32_e32 v13, 0xbfb8aa3b, v21
	v_mul_f32_e32 v14, 0xbfb8aa3b, v22
	v_mul_f32_e32 v15, 0xbfb8aa3b, v23
	v_exp_f32_e32 v12, v12
	v_exp_f32_e32 v13, v13
	v_exp_f32_e32 v14, v14
	v_exp_f32_e32 v15, v15
	v_add_f32_e32 v12, 1.0, v12
	v_add_f32_e32 v13, 1.0, v13
	v_add_f32_e32 v14, 1.0, v14
	v_add_f32_e32 v15, 1.0, v15
	v_rcp_f32_e32 v12, v12
	v_rcp_f32_e32 v13, v13
	v_rcp_f32_e32 v14, v14
	v_rcp_f32_e32 v15, v15
	v_mul_f32_e32 v12, v20, v12
	v_mul_f32_e32 v13, v21, v13
	v_mul_f32_e32 v14, v22, v14
	v_mul_f32_e32 v15, v23, v15
	v_mul_f32_e32 v12, v24, v12
	v_mul_f32_e32 v13, v25, v13
	v_mul_f32_e32 v14, v26, v14
	v_mul_f32_e32 v15, v27, v15
	v_cvt_pk_bf16_f32 v12, v12, v13
	v_cvt_pk_bf16_f32 v13, v14, v15
	global_store_dwordx2 v120, v[12:13], s[22:23]
	v_cmp_eq_u32_e64 s[72:73], 0, v123
	v_cmp_eq_u32_e64 s[74:75], 3, v123
	s_and_b64 s[72:73], s[72:73], s[36:37]
	s_and_b64 s[74:75], s[74:75], s[54:55]
	s_or_b64 vcc, s[72:73], s[74:75]
	v_cndmask_b32_e64 v28, v28, 0, vcc
	v_cndmask_b32_e64 v29, v29, 0, vcc
	v_cndmask_b32_e64 v30, v30, 0, vcc
	v_cndmask_b32_e64 v31, v31, 0, vcc
	v_fmac_f32_e32 v36, v32, v28
	v_fmac_f32_e32 v37, v33, v29
	v_fmac_f32_e32 v38, v34, v30
	v_fmac_f32_e32 v39, v35, v31
	v_mul_f32_e32 v28, 0xbfb8aa3b, v36
	v_mul_f32_e32 v29, 0xbfb8aa3b, v37
	v_mul_f32_e32 v30, 0xbfb8aa3b, v38
	v_mul_f32_e32 v31, 0xbfb8aa3b, v39
	v_exp_f32_e32 v28, v28
	v_exp_f32_e32 v29, v29
	v_exp_f32_e32 v30, v30
	v_exp_f32_e32 v31, v31
	v_add_f32_e32 v28, 1.0, v28
	v_add_f32_e32 v29, 1.0, v29
	v_add_f32_e32 v30, 1.0, v30
	v_add_f32_e32 v31, 1.0, v31
	v_rcp_f32_e32 v28, v28
	v_rcp_f32_e32 v29, v29
	v_rcp_f32_e32 v30, v30
	v_rcp_f32_e32 v31, v31
	v_mul_f32_e32 v28, v36, v28
	v_mul_f32_e32 v29, v37, v29
	v_mul_f32_e32 v30, v38, v30
	v_mul_f32_e32 v31, v39, v31
	v_mul_f32_e32 v28, v40, v28
	v_mul_f32_e32 v29, v41, v29
	v_mul_f32_e32 v30, v42, v30
	v_mul_f32_e32 v31, v43, v31
	v_cvt_pk_bf16_f32 v28, v28, v29
	v_cvt_pk_bf16_f32 v29, v30, v31
	global_store_dwordx2 v122, v[28:29], s[22:23]
	v_cmp_eq_u32_e64 s[72:73], 0, v125
	v_cmp_eq_u32_e64 s[74:75], 3, v125
	s_and_b64 s[72:73], s[72:73], s[36:37]
	s_and_b64 s[74:75], s[74:75], s[54:55]
	s_or_b64 vcc, s[72:73], s[74:75]
	v_cndmask_b32_e64 v44, v44, 0, vcc
	v_cndmask_b32_e64 v45, v45, 0, vcc
	v_cndmask_b32_e64 v46, v46, 0, vcc
	v_cndmask_b32_e64 v47, v47, 0, vcc
	v_fmac_f32_e32 v52, v48, v44
	v_fmac_f32_e32 v53, v49, v45
	v_fmac_f32_e32 v54, v50, v46
	v_fmac_f32_e32 v55, v51, v47
	v_mul_f32_e32 v44, 0xbfb8aa3b, v52
	v_mul_f32_e32 v45, 0xbfb8aa3b, v53
	v_mul_f32_e32 v46, 0xbfb8aa3b, v54
	v_mul_f32_e32 v47, 0xbfb8aa3b, v55
	v_exp_f32_e32 v44, v44
	v_exp_f32_e32 v45, v45
	v_exp_f32_e32 v46, v46
	v_exp_f32_e32 v47, v47
	v_add_f32_e32 v44, 1.0, v44
	v_add_f32_e32 v45, 1.0, v45
	v_add_f32_e32 v46, 1.0, v46
	v_add_f32_e32 v47, 1.0, v47
	v_rcp_f32_e32 v44, v44
	v_rcp_f32_e32 v45, v45
	v_rcp_f32_e32 v46, v46
	v_rcp_f32_e32 v47, v47
	v_mul_f32_e32 v44, v52, v44
	v_mul_f32_e32 v45, v53, v45
	v_mul_f32_e32 v46, v54, v46
	v_mul_f32_e32 v47, v55, v47
	v_mul_f32_e32 v44, v56, v44
	v_mul_f32_e32 v45, v57, v45
	v_mul_f32_e32 v46, v58, v46
	v_mul_f32_e32 v47, v59, v47
	v_cvt_pk_bf16_f32 v44, v44, v45
	v_cvt_pk_bf16_f32 v45, v46, v47
	global_store_dwordx2 v124, v[44:45], s[22:23]
	v_cmp_eq_u32_e64 s[72:73], 0, v127
	v_cmp_eq_u32_e64 s[74:75], 3, v127
	s_and_b64 s[72:73], s[72:73], s[36:37]
	s_and_b64 s[74:75], s[74:75], s[54:55]
	s_or_b64 vcc, s[72:73], s[74:75]
	v_cndmask_b32_e64 v60, v60, 0, vcc
	v_cndmask_b32_e64 v61, v61, 0, vcc
	v_cndmask_b32_e64 v62, v62, 0, vcc
	v_cndmask_b32_e64 v63, v63, 0, vcc
	v_fmac_f32_e32 v68, v64, v60
	v_fmac_f32_e32 v69, v65, v61
	v_fmac_f32_e32 v70, v66, v62
	v_fmac_f32_e32 v71, v67, v63
	v_mul_f32_e32 v60, 0xbfb8aa3b, v68
	v_mul_f32_e32 v61, 0xbfb8aa3b, v69
	v_mul_f32_e32 v62, 0xbfb8aa3b, v70
	v_mul_f32_e32 v63, 0xbfb8aa3b, v71
	v_exp_f32_e32 v60, v60
	v_exp_f32_e32 v61, v61
	v_exp_f32_e32 v62, v62
	v_exp_f32_e32 v63, v63
	v_add_f32_e32 v60, 1.0, v60
	v_add_f32_e32 v61, 1.0, v61
	v_add_f32_e32 v62, 1.0, v62
	v_add_f32_e32 v63, 1.0, v63
	v_rcp_f32_e32 v60, v60
	v_rcp_f32_e32 v61, v61
	v_rcp_f32_e32 v62, v62
	v_rcp_f32_e32 v63, v63
	v_mul_f32_e32 v60, v68, v60
	v_mul_f32_e32 v61, v69, v61
	v_mul_f32_e32 v62, v70, v62
	v_mul_f32_e32 v63, v71, v63
	v_mul_f32_e32 v60, v72, v60
	v_mul_f32_e32 v61, v73, v61
	v_mul_f32_e32 v62, v74, v62
	v_mul_f32_e32 v63, v75, v63
	v_cvt_pk_bf16_f32 v60, v60, v61
	v_cvt_pk_bf16_f32 v61, v62, v63
	global_store_dwordx2 v126, v[60:61], s[22:23]
	v_cmp_eq_u32_e64 s[72:73], 0, v129
	v_cmp_eq_u32_e64 s[74:75], 3, v129
	s_and_b64 s[72:73], s[72:73], s[36:37]
	s_and_b64 s[74:75], s[74:75], s[54:55]
	s_or_b64 vcc, s[72:73], s[74:75]
	v_cndmask_b32_e64 v88, v88, 0, vcc
	v_cndmask_b32_e64 v89, v89, 0, vcc
	v_cndmask_b32_e64 v90, v90, 0, vcc
	v_cndmask_b32_e64 v91, v91, 0, vcc
	v_fmac_f32_e32 v96, v92, v88
	v_fmac_f32_e32 v97, v93, v89
	v_fmac_f32_e32 v98, v94, v90
	v_fmac_f32_e32 v99, v95, v91
	v_mul_f32_e32 v88, 0xbfb8aa3b, v96
	v_mul_f32_e32 v89, 0xbfb8aa3b, v97
	v_mul_f32_e32 v90, 0xbfb8aa3b, v98
	v_mul_f32_e32 v91, 0xbfb8aa3b, v99
	v_exp_f32_e32 v88, v88
	v_exp_f32_e32 v89, v89
; DI float silu(float v) { return v * __builtin_amdgcn_rcpf(1.f + __builtin_amdgcn_exp2f(-1.4426950408889634f * v)); }
; DI void st_bf16x4(bf16_t* p, f32x4 v) { u32x2 w; w.x = cvt_pk_bf16(v[0], v[1]); w.y = cvt_pk_bf16(v[2], v[3]); *(u32x2*)p = w; }
; DI void glu_fix_panel(const Params& p, int l, int pm) {
;     ...
;     for (int it = tid_; it < 4 * (DFF / 4); it += 512) {
;         const int col = (it % (DFF / 4)) * 4, e = it / (DFF / 4);
;         f32x4 nb = (f32x4){0.f, 0.f, 0.f, 0.f}; int tap; int tok;
;         if (e == 0) { tap = 0; tok = 0; if (!(pr == 0 || pr == 1)) nb = *(const f32x4*)(EA + ((size_t)(pm - 1) * 4 + 3) * DFF + col); }
;         else if (e == 1) { tap = 2; tok = 127; nb = *(const f32x4*)(EA + ((size_t)pm * 4 + 2) * DFF + col); }
;         else if (e == 2) { tap = 0; tok = 128; nb = *(const f32x4*)(EA + ((size_t)pm * 4 + 1) * DFF + col); }
;         else { tap = 2; tok = 255; if (!(pr == 0 || pr == 8)) nb = *(const f32x4*)(EA + ((size_t)(pm + 1) * 4 + 0) * DFF + col); }
;         const f32x4 w = *(const f32x4*)(cw + (size_t)tap * DFF + col);
;         const size_t eo = ((size_t)pm * 4 + e) * DFF + col;
;         const f32x4 pp = *(const f32x4*)(EP + eo), uu = *(const f32x4*)(EU + eo);
;         f32x4 g;
; #pragma unroll
;         for (int j = 0; j < 4; ++j) g[j] = silu(pp[j] + w[j] * nb[j]) * uu[j];
;         st_bf16x4(G + ((size_t)pm * BM + tok) * DFF + col, g);
	v_exp_f32_e32 v90, v90
	v_exp_f32_e32 v91, v91
	v_add_f32_e32 v88, 1.0, v88
	v_add_f32_e32 v89, 1.0, v89
	v_add_f32_e32 v90, 1.0, v90
	v_add_f32_e32 v91, 1.0, v91
	v_rcp_f32_e32 v88, v88
	v_rcp_f32_e32 v89, v89
	v_rcp_f32_e32 v90, v90
	v_rcp_f32_e32 v91, v91
	v_mul_f32_e32 v88, v96, v88
	v_mul_f32_e32 v89, v97, v89
	v_mul_f32_e32 v90, v98, v90
	v_mul_f32_e32 v91, v99, v91
	v_mul_f32_e32 v88, v100, v88
	v_mul_f32_e32 v89, v101, v89
	v_mul_f32_e32 v90, v102, v90
	v_mul_f32_e32 v91, v103, v91
	v_cvt_pk_bf16_f32 v88, v88, v89
	v_cvt_pk_bf16_f32 v89, v90, v91
	global_store_dwordx2 v128, v[88:89], s[22:23]
	v_cmp_eq_u32_e64 s[72:73], 0, v131
	v_cmp_eq_u32_e64 s[74:75], 3, v131
	s_and_b64 s[72:73], s[72:73], s[36:37]
	s_and_b64 s[74:75], s[74:75], s[54:55]
	s_or_b64 vcc, s[72:73], s[74:75]
	v_cndmask_b32_e64 v104, v104, 0, vcc
	v_cndmask_b32_e64 v105, v105, 0, vcc
	v_cndmask_b32_e64 v106, v106, 0, vcc
	v_cndmask_b32_e64 v107, v107, 0, vcc
	v_fmac_f32_e32 v112, v108, v104
	v_fmac_f32_e32 v113, v109, v105
	v_fmac_f32_e32 v114, v110, v106
	v_fmac_f32_e32 v115, v111, v107
	v_mul_f32_e32 v104, 0xbfb8aa3b, v112
	v_mul_f32_e32 v105, 0xbfb8aa3b, v113
	v_mul_f32_e32 v106, 0xbfb8aa3b, v114
	v_mul_f32_e32 v107, 0xbfb8aa3b, v115
	v_exp_f32_e32 v104, v104
	v_exp_f32_e32 v105, v105
	v_exp_f32_e32 v106, v106
	v_exp_f32_e32 v107, v107
	v_add_f32_e32 v104, 1.0, v104
	v_add_f32_e32 v105, 1.0, v105
	v_add_f32_e32 v106, 1.0, v106
	v_add_f32_e32 v107, 1.0, v107
	v_rcp_f32_e32 v104, v104
	v_rcp_f32_e32 v105, v105
	v_rcp_f32_e32 v106, v106
	v_rcp_f32_e32 v107, v107
	v_mul_f32_e32 v104, v112, v104
	v_mul_f32_e32 v105, v113, v105
	v_mul_f32_e32 v106, v114, v106
	v_mul_f32_e32 v107, v115, v107
	v_mul_f32_e32 v104, v116, v104
	v_mul_f32_e32 v105, v117, v105
	v_mul_f32_e32 v106, v118, v106
	v_mul_f32_e32 v107, v119, v107
	v_cvt_pk_bf16_f32 v104, v104, v105
	v_cvt_pk_bf16_f32 v105, v106, v107
	global_store_dwordx2 v130, v[104:105], s[22:23]
	v_add_u32_e32 v140, 0xc00, v202
	v_mul_hi_u32 v121, v140, s27
	v_mul_u32_u24_e32 v142, 0x580, v121
	v_sub_u32_e32 v141, v140, v142
	v_mul_u32_u24_e32 v142, 0x5800, v121
	v_lshl_add_u32 v145, v141, 4, v142
	v_and_b32_e32 v144, 1, v121
	v_mul_u32_u24_e32 v143, 0xb000, v144
	v_add_u32_e32 v146, v143, v145
	v_add_u32_e32 v148, 0x5800, v145
	v_lshl_add_u32 v147, v141, 4, v143
	v_lshrrev_b32_e32 v149, 1, v121
	v_mul_u32_u24_e32 v149, 0x160000, v149
	v_mul_u32_u24_e32 v150, 0x15d400, v144
	v_lshlrev_b32_e32 v142, 3, v141
	v_add3_u32 v120, v149, v150, v142
	v_cmp_eq_u32_e64 s[72:73], 0, v121
	v_cmp_eq_u32_e64 s[74:75], 3, v121
	s_and_b64 s[72:73], s[72:73], s[36:37]
	s_and_b64 s[74:75], s[74:75], s[54:55]
	s_or_b64 vcc, s[72:73], s[74:75]
	v_cndmask_b32_e32 v146, v146, v148, vcc
	global_load_dwordx4 v[12:15], v146, s[6:7]
	global_load_dwordx4 v[16:19], v147, s[38:39]
	global_load_dwordx4 v[20:23], v145, s[2:3]
	global_load_dwordx4 v[24:27], v145, s[4:5]
	v_add_u32_e32 v140, 0xe00, v202
	v_mul_hi_u32 v123, v140, s27
	v_mul_u32_u24_e32 v142, 0x580, v123
	v_sub_u32_e32 v141, v140, v142
	v_mul_u32_u24_e32 v142, 0x5800, v123
	v_lshl_add_u32 v145, v141, 4, v142
	v_and_b32_e32 v144, 1, v123
	v_mul_u32_u24_e32 v143, 0xb000, v144
	v_add_u32_e32 v146, v143, v145
	v_add_u32_e32 v148, 0x5800, v145
	v_lshl_add_u32 v147, v141, 4, v143
	v_lshrrev_b32_e32 v149, 1, v123
	v_mul_u32_u24_e32 v149, 0x160000, v149
	v_mul_u32_u24_e32 v150, 0x15d400, v144
	v_lshlrev_b32_e32 v142, 3, v141
	v_add3_u32 v122, v149, v150, v142
	v_cmp_eq_u32_e64 s[72:73], 0, v123
	v_cmp_eq_u32_e64 s[74:75], 3, v123
	s_and_b64 s[72:73], s[72:73], s[36:37]
	s_and_b64 s[74:75], s[74:75], s[54:55]
	s_or_b64 vcc, s[72:73], s[74:75]
	v_cndmask_b32_e32 v146, v146, v148, vcc
	global_load_dwordx4 v[28:31], v146, s[6:7]
	global_load_dwordx4 v[32:35], v147, s[38:39]
	global_load_dwordx4 v[36:39], v145, s[2:3]
	global_load_dwordx4 v[40:43], v145, s[4:5]
	v_add_u32_e32 v140, 0x1000, v202
	v_mul_hi_u32 v125, v140, s27
	v_mul_u32_u24_e32 v142, 0x580, v125
	v_sub_u32_e32 v141, v140, v142
	v_mul_u32_u24_e32 v142, 0x5800, v125
	v_lshl_add_u32 v145, v141, 4, v142
	v_and_b32_e32 v144, 1, v125
	v_mul_u32_u24_e32 v143, 0xb000, v144
	v_add_u32_e32 v146, v143, v145
	v_add_u32_e32 v148, 0x5800, v145
	v_lshl_add_u32 v147, v141, 4, v143
	v_lshrrev_b32_e32 v149, 1, v125
	v_mul_u32_u24_e32 v149, 0x160000, v149
	v_mul_u32_u24_e32 v150, 0x15d400, v144
	v_lshlrev_b32_e32 v142, 3, v141
	v_add3_u32 v124, v149, v150, v142
	v_cmp_eq_u32_e64 s[72:73], 0, v125
	v_cmp_eq_u32_e64 s[74:75], 3, v125
	s_and_b64 s[72:73], s[72:73], s[36:37]
	s_and_b64 s[74:75], s[74:75], s[54:55]
	s_or_b64 vcc, s[72:73], s[74:75]
	v_cndmask_b32_e32 v146, v146, v148, vcc
	global_load_dwordx4 v[44:47], v146, s[6:7]
	global_load_dwordx4 v[48:51], v147, s[38:39]
	global_load_dwordx4 v[52:55], v145, s[2:3]
	global_load_dwordx4 v[56:59], v145, s[4:5]
	v_add_u32_e32 v140, 0x1200, v202
	v_mul_hi_u32 v127, v140, s27
	v_mul_u32_u24_e32 v142, 0x580, v127
	v_sub_u32_e32 v141, v140, v142
	v_mul_u32_u24_e32 v142, 0x5800, v127
	v_lshl_add_u32 v145, v141, 4, v142
	v_and_b32_e32 v144, 1, v127
	v_mul_u32_u24_e32 v143, 0xb000, v144
	v_add_u32_e32 v146, v143, v145
	v_add_u32_e32 v148, 0x5800, v145
	v_lshl_add_u32 v147, v141, 4, v143
	v_lshrrev_b32_e32 v149, 1, v127
	v_mul_u32_u24_e32 v149, 0x160000, v149
	v_mul_u32_u24_e32 v150, 0x15d400, v144
	v_lshlrev_b32_e32 v142, 3, v141
	v_add3_u32 v126, v149, v150, v142
	v_cmp_eq_u32_e64 s[72:73], 0, v127
	v_cmp_eq_u32_e64 s[74:75], 3, v127
	s_and_b64 s[72:73], s[72:73], s[36:37]
	s_and_b64 s[74:75], s[74:75], s[54:55]
	s_or_b64 vcc, s[72:73], s[74:75]
	v_cndmask_b32_e32 v146, v146, v148, vcc
	global_load_dwordx4 v[60:63], v146, s[6:7]
	global_load_dwordx4 v[64:67], v147, s[38:39]
	global_load_dwordx4 v[68:71], v145, s[2:3]
	global_load_dwordx4 v[72:75], v145, s[4:5]
	v_add_u32_e32 v140, 0x1400, v202
	v_mul_hi_u32 v129, v140, s27
	v_mul_u32_u24_e32 v142, 0x580, v129
	v_sub_u32_e32 v141, v140, v142
	v_mul_u32_u24_e32 v142, 0x5800, v129
	v_lshl_add_u32 v145, v141, 4, v142
	v_and_b32_e32 v144, 1, v129
	v_mul_u32_u24_e32 v143, 0xb000, v144
	v_add_u32_e32 v146, v143, v145
	v_add_u32_e32 v148, 0x5800, v145
	v_lshl_add_u32 v147, v141, 4, v143
	v_lshrrev_b32_e32 v149, 1, v129
	v_mul_u32_u24_e32 v149, 0x160000, v149
	v_mul_u32_u24_e32 v150, 0x15d400, v144
	v_lshlrev_b32_e32 v142, 3, v141
	v_add3_u32 v128, v149, v150, v142
	v_cmp_eq_u32_e64 s[72:73], 0, v129
	v_cmp_eq_u32_e64 s[74:75], 3, v129
	s_and_b64 s[72:73], s[72:73], s[36:37]
	s_and_b64 s[74:75], s[74:75], s[54:55]
	s_or_b64 vcc, s[72:73], s[74:75]
	v_cndmask_b32_e32 v146, v146, v148, vcc
	global_load_dwordx4 v[88:91], v146, s[6:7]
	global_load_dwordx4 v[92:95], v147, s[38:39]
	global_load_dwordx4 v[96:99], v145, s[2:3]
	global_load_dwordx4 v[100:103], v145, s[4:5]
	s_waitcnt vmcnt(0)
; DI float silu(float v) { return v * __builtin_amdgcn_rcpf(1.f + __builtin_amdgcn_exp2f(-1.4426950408889634f * v)); }
; DI void st_bf16x4(bf16_t* p, f32x4 v) { u32x2 w; w.x = cvt_pk_bf16(v[0], v[1]); w.y = cvt_pk_bf16(v[2], v[3]); *(u32x2*)p = w; }
; DI void glu_fix_panel(const Params& p, int l, int pm) {
;     ...
;         f32x4 nb = (f32x4){0.f, 0.f, 0.f, 0.f}; int tap; int tok;
;         if (e == 0) { tap = 0; tok = 0; if (!(pr == 0 || pr == 1)) nb = *(const f32x4*)(EA + ((size_t)(pm - 1) * 4 + 3) * DFF + col); }
;         else if (e == 1) { tap = 2; tok = 127; nb = *(const f32x4*)(EA + ((size_t)pm * 4 + 2) * DFF + col); }
;         else if (e == 2) { tap = 0; tok = 128; nb = *(const f32x4*)(EA + ((size_t)pm * 4 + 1) * DFF + col); }
;         else { tap = 2; tok = 255; if (!(pr == 0 || pr == 8)) nb = *(const f32x4*)(EA + ((size_t)(pm + 1) * 4 + 0) * DFF + col); }
;         const f32x4 w = *(const f32x4*)(cw + (size_t)tap * DFF + col);
;         const size_t eo = ((size_t)pm * 4 + e) * DFF + col;
;         const f32x4 pp = *(const f32x4*)(EP + eo), uu = *(const f32x4*)(EU + eo);
;         f32x4 g;
; #pragma unroll
;         for (int j = 0; j < 4; ++j) g[j] = silu(pp[j] + w[j] * nb[j]) * uu[j];
;         st_bf16x4(G + ((size_t)pm * BM + tok) * DFF + col, g);
	v_cmp_eq_u32_e64 s[72:73], 0, v121
	v_cmp_eq_u32_e64 s[74:75], 3, v121
	s_and_b64 s[72:73], s[72:73], s[36:37]
	s_and_b64 s[74:75], s[74:75], s[54:55]
	s_or_b64 vcc, s[72:73], s[74:75]
	v_cndmask_b32_e64 v12, v12, 0, vcc
	v_cndmask_b32_e64 v13, v13, 0, vcc
	v_cndmask_b32_e64 v14, v14, 0, vcc
	v_cndmask_b32_e64 v15, v15, 0, vcc
	v_fmac_f32_e32 v20, v16, v12
	v_fmac_f32_e32 v21, v17, v13
	v_fmac_f32_e32 v22, v18, v14
	v_fmac_f32_e32 v23, v19, v15
	v_mul_f32_e32 v12, 0xbfb8aa3b, v20
	v_mul_f32_e32 v13, 0xbfb8aa3b, v21
	v_mul_f32_e32 v14, 0xbfb8aa3b, v22
	v_mul_f32_e32 v15, 0xbfb8aa3b, v23
	v_exp_f32_e32 v12, v12
	v_exp_f32_e32 v13, v13
	v_exp_f32_e32 v14, v14
	v_exp_f32_e32 v15, v15
	v_add_f32_e32 v12, 1.0, v12
	v_add_f32_e32 v13, 1.0, v13
	v_add_f32_e32 v14, 1.0, v14
	v_add_f32_e32 v15, 1.0, v15
	v_rcp_f32_e32 v12, v12
	v_rcp_f32_e32 v13, v13
	v_rcp_f32_e32 v14, v14
	v_rcp_f32_e32 v15, v15
	v_mul_f32_e32 v12, v20, v12
	v_mul_f32_e32 v13, v21, v13
	v_mul_f32_e32 v14, v22, v14
	v_mul_f32_e32 v15, v23, v15
	v_mul_f32_e32 v12, v24, v12
	v_mul_f32_e32 v13, v25, v13
	v_mul_f32_e32 v14, v26, v14
	v_mul_f32_e32 v15, v27, v15
	v_cvt_pk_bf16_f32 v12, v12, v13
	v_cvt_pk_bf16_f32 v13, v14, v15
	global_store_dwordx2 v120, v[12:13], s[22:23]
	v_cmp_eq_u32_e64 s[72:73], 0, v123
	v_cmp_eq_u32_e64 s[74:75], 3, v123
	s_and_b64 s[72:73], s[72:73], s[36:37]
	s_and_b64 s[74:75], s[74:75], s[54:55]
	s_or_b64 vcc, s[72:73], s[74:75]
	v_cndmask_b32_e64 v28, v28, 0, vcc
	v_cndmask_b32_e64 v29, v29, 0, vcc
	v_cndmask_b32_e64 v30, v30, 0, vcc
	v_cndmask_b32_e64 v31, v31, 0, vcc
	v_fmac_f32_e32 v36, v32, v28
	v_fmac_f32_e32 v37, v33, v29
	v_fmac_f32_e32 v38, v34, v30
	v_fmac_f32_e32 v39, v35, v31
	v_mul_f32_e32 v28, 0xbfb8aa3b, v36
	v_mul_f32_e32 v29, 0xbfb8aa3b, v37
	v_mul_f32_e32 v30, 0xbfb8aa3b, v38
	v_mul_f32_e32 v31, 0xbfb8aa3b, v39
	v_exp_f32_e32 v28, v28
	v_exp_f32_e32 v29, v29
	v_exp_f32_e32 v30, v30
	v_exp_f32_e32 v31, v31
	v_add_f32_e32 v28, 1.0, v28
	v_add_f32_e32 v29, 1.0, v29
	v_add_f32_e32 v30, 1.0, v30
	v_add_f32_e32 v31, 1.0, v31
	v_rcp_f32_e32 v28, v28
	v_rcp_f32_e32 v29, v29
	v_rcp_f32_e32 v30, v30
	v_rcp_f32_e32 v31, v31
	v_mul_f32_e32 v28, v36, v28
	v_mul_f32_e32 v29, v37, v29
	v_mul_f32_e32 v30, v38, v30
	v_mul_f32_e32 v31, v39, v31
	v_mul_f32_e32 v28, v40, v28
	v_mul_f32_e32 v29, v41, v29
	v_mul_f32_e32 v30, v42, v30
	v_mul_f32_e32 v31, v43, v31
	v_cvt_pk_bf16_f32 v28, v28, v29
	v_cvt_pk_bf16_f32 v29, v30, v31
	global_store_dwordx2 v122, v[28:29], s[22:23]
	v_cmp_eq_u32_e64 s[72:73], 0, v125
	v_cmp_eq_u32_e64 s[74:75], 3, v125
	s_and_b64 s[72:73], s[72:73], s[36:37]
	s_and_b64 s[74:75], s[74:75], s[54:55]
	s_or_b64 vcc, s[72:73], s[74:75]
	v_cndmask_b32_e64 v44, v44, 0, vcc
	v_cndmask_b32_e64 v45, v45, 0, vcc
	v_cndmask_b32_e64 v46, v46, 0, vcc
	v_cndmask_b32_e64 v47, v47, 0, vcc
	v_fmac_f32_e32 v52, v48, v44
	v_fmac_f32_e32 v53, v49, v45
	v_fmac_f32_e32 v54, v50, v46
	v_fmac_f32_e32 v55, v51, v47
	v_mul_f32_e32 v44, 0xbfb8aa3b, v52
	v_mul_f32_e32 v45, 0xbfb8aa3b, v53
	v_mul_f32_e32 v46, 0xbfb8aa3b, v54
	v_mul_f32_e32 v47, 0xbfb8aa3b, v55
	v_exp_f32_e32 v44, v44
	v_exp_f32_e32 v45, v45
	v_exp_f32_e32 v46, v46
	v_exp_f32_e32 v47, v47
	v_add_f32_e32 v44, 1.0, v44
	v_add_f32_e32 v45, 1.0, v45
	v_add_f32_e32 v46, 1.0, v46
	v_add_f32_e32 v47, 1.0, v47
	v_rcp_f32_e32 v44, v44
	v_rcp_f32_e32 v45, v45
	v_rcp_f32_e32 v46, v46
	v_rcp_f32_e32 v47, v47
	v_mul_f32_e32 v44, v52, v44
	v_mul_f32_e32 v45, v53, v45
	v_mul_f32_e32 v46, v54, v46
	v_mul_f32_e32 v47, v55, v47
	v_mul_f32_e32 v44, v56, v44
	v_mul_f32_e32 v45, v57, v45
	v_mul_f32_e32 v46, v58, v46
	v_mul_f32_e32 v47, v59, v47
	v_cvt_pk_bf16_f32 v44, v44, v45
	v_cvt_pk_bf16_f32 v45, v46, v47
	global_store_dwordx2 v124, v[44:45], s[22:23]
	v_cmp_eq_u32_e64 s[72:73], 0, v127
	v_cmp_eq_u32_e64 s[74:75], 3, v127
	s_and_b64 s[72:73], s[72:73], s[36:37]
	s_and_b64 s[74:75], s[74:75], s[54:55]
	s_or_b64 vcc, s[72:73], s[74:75]
	v_cndmask_b32_e64 v60, v60, 0, vcc
	v_cndmask_b32_e64 v61, v61, 0, vcc
	v_cndmask_b32_e64 v62, v62, 0, vcc
	v_cndmask_b32_e64 v63, v63, 0, vcc
	v_fmac_f32_e32 v68, v64, v60
	v_fmac_f32_e32 v69, v65, v61
	v_fmac_f32_e32 v70, v66, v62
	v_fmac_f32_e32 v71, v67, v63
	v_mul_f32_e32 v60, 0xbfb8aa3b, v68
	v_mul_f32_e32 v61, 0xbfb8aa3b, v69
	v_mul_f32_e32 v62, 0xbfb8aa3b, v70
	v_mul_f32_e32 v63, 0xbfb8aa3b, v71
	v_exp_f32_e32 v60, v60
	v_exp_f32_e32 v61, v61
	v_exp_f32_e32 v62, v62
	v_exp_f32_e32 v63, v63
	v_add_f32_e32 v60, 1.0, v60
	v_add_f32_e32 v61, 1.0, v61
	v_add_f32_e32 v62, 1.0, v62
	v_add_f32_e32 v63, 1.0, v63
	v_rcp_f32_e32 v60, v60
	v_rcp_f32_e32 v61, v61
	v_rcp_f32_e32 v62, v62
	v_rcp_f32_e32 v63, v63
	v_mul_f32_e32 v60, v68, v60
	v_mul_f32_e32 v61, v69, v61
	v_mul_f32_e32 v62, v70, v62
	v_mul_f32_e32 v63, v71, v63
	v_mul_f32_e32 v60, v72, v60
	v_mul_f32_e32 v61, v73, v61
	v_mul_f32_e32 v62, v74, v62
	v_mul_f32_e32 v63, v75, v63
	v_cvt_pk_bf16_f32 v60, v60, v61
	v_cvt_pk_bf16_f32 v61, v62, v63
	global_store_dwordx2 v126, v[60:61], s[22:23]
	v_cmp_eq_u32_e64 s[72:73], 0, v129
	v_cmp_eq_u32_e64 s[74:75], 3, v129
	s_and_b64 s[72:73], s[72:73], s[36:37]
	s_and_b64 s[74:75], s[74:75], s[54:55]
	s_or_b64 vcc, s[72:73], s[74:75]
	v_cndmask_b32_e64 v88, v88, 0, vcc
	v_cndmask_b32_e64 v89, v89, 0, vcc
	v_cndmask_b32_e64 v90, v90, 0, vcc
	v_cndmask_b32_e64 v91, v91, 0, vcc
	v_fmac_f32_e32 v96, v92, v88
	v_fmac_f32_e32 v97, v93, v89
	v_fmac_f32_e32 v98, v94, v90
	v_fmac_f32_e32 v99, v95, v91
	v_mul_f32_e32 v88, 0xbfb8aa3b, v96
	v_mul_f32_e32 v89, 0xbfb8aa3b, v97
	v_mul_f32_e32 v90, 0xbfb8aa3b, v98
	v_mul_f32_e32 v91, 0xbfb8aa3b, v99
	v_exp_f32_e32 v88, v88
	v_exp_f32_e32 v89, v89
	v_exp_f32_e32 v90, v90
	v_exp_f32_e32 v91, v91
	v_add_f32_e32 v88, 1.0, v88
	v_add_f32_e32 v89, 1.0, v89
	v_add_f32_e32 v90, 1.0, v90
	v_add_f32_e32 v91, 1.0, v91
	v_rcp_f32_e32 v88, v88
	v_rcp_f32_e32 v89, v89
	v_rcp_f32_e32 v90, v90
	v_rcp_f32_e32 v91, v91
	v_mul_f32_e32 v88, v96, v88
	v_mul_f32_e32 v89, v97, v89
	v_mul_f32_e32 v90, v98, v90
	v_mul_f32_e32 v91, v99, v91
	v_mul_f32_e32 v88, v100, v88
	v_mul_f32_e32 v89, v101, v89
	v_mul_f32_e32 v90, v102, v90
	v_mul_f32_e32 v91, v103, v91
	v_cvt_pk_bf16_f32 v88, v88, v89
	v_cvt_pk_bf16_f32 v89, v90, v91
	global_store_dwordx2 v128, v[88:89], s[22:23]

; DI int otid() { int t = threadIdx.x; asm volatile("" : "+v"(t)); return t; }
;     DI bool next(int i, Unit& u) const {
;     ...
;         int wgid = (int)L; { const int q = nwg / NXCD, r = nwg % NXCD, xcd = wgid % NXCD, off = wgid / NXCD; wgid = (xcd < r ? xcd * (q + 1) : r * (q + 1) + (xcd - r) * q) + off; }
;         const int nig = WGM * nN, gid = wgid / nig, fm = gid * WGM, gsz = (nM - fm) < WGM ? (nM - fm) : WGM;
;         int pm = fm + ((wgid % nig) % gsz); u.pn = (wgid % nig) / gsz;
;         if (skip_ctx) pm = (pm >> 3) * 9 + 1 + (pm & 7);
; DI void glu_fix_panel(const Params& p, int l, int pm) {
;     ...
;     bf16_t* G = (bf16_t*)(ws + WS_G);
;     const float* EA = (const float*)(ws + WS_EDGE); const float* EP = EA + (size_t)36 * 4 * DFF; const float* EU = EP + (size_t)36 * 4 * DFF;
;     const float* cw = p.in[17] + (size_t)l * 3 * DFF;
;     const int tid_ = otid();
;     const int pr = pm % 9;
;     for (int it = tid_; it < 4 * (DFF / 4); it += 512) {
;         const int col = (it % (DFF / 4)) * 4, e = it / (DFF / 4);
;         f32x4 nb = (f32x4){0.f, 0.f, 0.f, 0.f}; int tap; int tok;
;         if (e == 0) { tap = 0; tok = 0; if (!(pr == 0 || pr == 1)) nb = *(const f32x4*)(EA + ((size_t)(pm - 1) * 4 + 3) * DFF + col); }
;         else if (e == 1) { tap = 2; tok = 127; nb = *(const f32x4*)(EA + ((size_t)pm * 4 + 2) * DFF + col); }
;         else if (e == 2) { tap = 0; tok = 128; nb = *(const f32x4*)(EA + ((size_t)pm * 4 + 1) * DFF + col); }
;         else { tap = 2; tok = 255; if (!(pr == 0 || pr == 8)) nb = *(const f32x4*)(EA + ((size_t)(pm + 1) * 4 + 0) * DFF + col); }
;         const f32x4 w = *(const f32x4*)(cw + (size_t)tap * DFF + col);
;         const size_t eo = ((size_t)pm * 4 + e) * DFF + col;
;         const f32x4 pp = *(const f32x4*)(EP + eo), uu = *(const f32x4*)(EU + eo);
.LBB0_3049:
	s_and_b32 s29, s26, 7
	s_lshr_b32 s29, s29, 1
	s_mul_i32 s29, s29, 9
	s_lshr_b32 s9, s26, 3
	s_and_b32 s9, s9, 7
	s_add_u32 s9, s9, s29
	s_add_u32 s9, s9, 1
	s_mul_i32 s29, s9, 57
	s_lshr_b32 s29, s29, 9
	s_mul_i32 s29, s29, 9
	s_sub_u32 s11, s9, s29
	s_cmp_lt_u32 s11, 2
	s_cselect_b64 s[36:37], -1, 0
	s_cmp_eq_u32 s11, 0
	s_cselect_b64 s[72:73], -1, 0
	s_cmp_eq_u32 s11, 8
	s_cselect_b64 s[54:55], -1, 0
	s_or_b64 s[54:55], s[54:55], s[72:73]
	s_mul_i32 s29, s9, 0x16000
	s_add_u32 s2, s50, 0x116b8000
	s_addc_u32 s3, s51, 0
	s_add_u32 s2, s2, s29
	s_addc_u32 s3, s3, 0
	s_add_u32 s4, s50, 0x119d0000
	s_addc_u32 s5, s51, 0
	s_add_u32 s4, s4, s29
	s_addc_u32 s5, s5, 0
	s_add_u32 s6, s50, 0x113a0000
	s_addc_u32 s7, s51, 0
	s_add_u32 s6, s6, s29
	s_addc_u32 s7, s7, 0
	s_sub_u32 s6, s6, 0x5800
	s_subb_u32 s7, s7, 0
	s_mul_i32 s29, s9, 0x2c0000
	s_add_u32 s22, s50, 0x1d9a0000
	s_addc_u32 s23, s51, 0
	s_add_u32 s22, s22, s29
	s_addc_u32 s23, s23, 0
	s_mov_b32 s27, 0x2e8ba3
	v_mov_b32_e32 v140, v202
	v_mul_hi_u32 v121, v140, s27
	v_mul_u32_u24_e32 v142, 0x580, v121
	v_sub_u32_e32 v141, v140, v142
	v_mul_u32_u24_e32 v142, 0x5800, v121
	v_lshl_add_u32 v145, v141, 4, v142
	v_and_b32_e32 v144, 1, v121
	v_mul_u32_u24_e32 v143, 0xb000, v144
	v_add_u32_e32 v146, v143, v145
	v_add_u32_e32 v148, 0x5800, v145
	v_lshl_add_u32 v147, v141, 4, v143
	v_lshrrev_b32_e32 v149, 1, v121
	v_mul_u32_u24_e32 v149, 0x160000, v149
	v_mul_u32_u24_e32 v150, 0x15d400, v144
	v_lshlrev_b32_e32 v142, 3, v141
	v_add3_u32 v120, v149, v150, v142
	v_cmp_eq_u32_e64 s[72:73], 0, v121
	v_cmp_eq_u32_e64 s[74:75], 3, v121
	s_and_b64 s[72:73], s[72:73], s[36:37]
	s_and_b64 s[74:75], s[74:75], s[54:55]
	s_or_b64 vcc, s[72:73], s[74:75]
	v_cndmask_b32_e32 v146, v146, v148, vcc
	global_load_dwordx4 v[12:15], v146, s[6:7]
	global_load_dwordx4 v[16:19], v147, s[0:1]
	global_load_dwordx4 v[20:23], v145, s[2:3]
	global_load_dwordx4 v[24:27], v145, s[4:5]
	v_add_u32_e32 v140, 0x200, v202
	v_mul_hi_u32 v123, v140, s27
	v_mul_u32_u24_e32 v142, 0x580, v123
	v_sub_u32_e32 v141, v140, v142
	v_mul_u32_u24_e32 v142, 0x5800, v123
	v_lshl_add_u32 v145, v141, 4, v142
	v_and_b32_e32 v144, 1, v123
	v_mul_u32_u24_e32 v143, 0xb000, v144
	v_add_u32_e32 v146, v143, v145
	v_add_u32_e32 v148, 0x5800, v145
	v_lshl_add_u32 v147, v141, 4, v143
	v_lshrrev_b32_e32 v149, 1, v123
	v_mul_u32_u24_e32 v149, 0x160000, v149
	v_mul_u32_u24_e32 v150, 0x15d400, v144
	v_lshlrev_b32_e32 v142, 3, v141
	v_add3_u32 v122, v149, v150, v142
	v_cmp_eq_u32_e64 s[72:73], 0, v123
	v_cmp_eq_u32_e64 s[74:75], 3, v123
	s_and_b64 s[72:73], s[72:73], s[36:37]
	s_and_b64 s[74:75], s[74:75], s[54:55]
	s_or_b64 vcc, s[72:73], s[74:75]
	v_cndmask_b32_e32 v146, v146, v148, vcc
	global_load_dwordx4 v[28:31], v146, s[6:7]
	global_load_dwordx4 v[32:35], v147, s[0:1]
	global_load_dwordx4 v[36:39], v145, s[2:3]
	global_load_dwordx4 v[40:43], v145, s[4:5]
	v_add_u32_e32 v140, 0x400, v202
	v_mul_hi_u32 v125, v140, s27
	v_mul_u32_u24_e32 v142, 0x580, v125
	v_sub_u32_e32 v141, v140, v142
	v_mul_u32_u24_e32 v142, 0x5800, v125
	v_lshl_add_u32 v145, v141, 4, v142
	v_and_b32_e32 v144, 1, v125
	v_mul_u32_u24_e32 v143, 0xb000, v144
	v_add_u32_e32 v146, v143, v145
	v_add_u32_e32 v148, 0x5800, v145
	v_lshl_add_u32 v147, v141, 4, v143
	v_lshrrev_b32_e32 v149, 1, v125
	v_mul_u32_u24_e32 v149, 0x160000, v149
	v_mul_u32_u24_e32 v150, 0x15d400, v144
	v_lshlrev_b32_e32 v142, 3, v141
	v_add3_u32 v124, v149, v150, v142
	v_cmp_eq_u32_e64 s[72:73], 0, v125
	v_cmp_eq_u32_e64 s[74:75], 3, v125
	s_and_b64 s[72:73], s[72:73], s[36:37]
	s_and_b64 s[74:75], s[74:75], s[54:55]
	s_or_b64 vcc, s[72:73], s[74:75]
	v_cndmask_b32_e32 v146, v146, v148, vcc
	global_load_dwordx4 v[44:47], v146, s[6:7]
	global_load_dwordx4 v[48:51], v147, s[0:1]
	global_load_dwordx4 v[52:55], v145, s[2:3]
	global_load_dwordx4 v[56:59], v145, s[4:5]
	v_add_u32_e32 v140, 0x600, v202
	v_mul_hi_u32 v127, v140, s27
	v_mul_u32_u24_e32 v142, 0x580, v127
	v_sub_u32_e32 v141, v140, v142
	v_mul_u32_u24_e32 v142, 0x5800, v127
	v_lshl_add_u32 v145, v141, 4, v142
	v_and_b32_e32 v144, 1, v127
	v_mul_u32_u24_e32 v143, 0xb000, v144
	v_add_u32_e32 v146, v143, v145
	v_add_u32_e32 v148, 0x5800, v145
	v_lshl_add_u32 v147, v141, 4, v143
	v_lshrrev_b32_e32 v149, 1, v127
	v_mul_u32_u24_e32 v149, 0x160000, v149
	v_mul_u32_u24_e32 v150, 0x15d400, v144
	v_lshlrev_b32_e32 v142, 3, v141
	v_add3_u32 v126, v149, v150, v142
	v_cmp_eq_u32_e64 s[72:73], 0, v127
	v_cmp_eq_u32_e64 s[74:75], 3, v127
	s_and_b64 s[72:73], s[72:73], s[36:37]
	s_and_b64 s[74:75], s[74:75], s[54:55]
	s_or_b64 vcc, s[72:73], s[74:75]
	v_cndmask_b32_e32 v146, v146, v148, vcc
	global_load_dwordx4 v[60:63], v146, s[6:7]
	global_load_dwordx4 v[64:67], v147, s[0:1]
	global_load_dwordx4 v[68:71], v145, s[2:3]
	global_load_dwordx4 v[72:75], v145, s[4:5]
	v_add_u32_e32 v140, 0x800, v202
	v_mul_hi_u32 v129, v140, s27
	v_mul_u32_u24_e32 v142, 0x580, v129
	v_sub_u32_e32 v141, v140, v142
	v_mul_u32_u24_e32 v142, 0x5800, v129
	v_lshl_add_u32 v145, v141, 4, v142
	v_and_b32_e32 v144, 1, v129
	v_mul_u32_u24_e32 v143, 0xb000, v144
	v_add_u32_e32 v146, v143, v145
	v_add_u32_e32 v148, 0x5800, v145
	v_lshl_add_u32 v147, v141, 4, v143
	v_lshrrev_b32_e32 v149, 1, v129
	v_mul_u32_u24_e32 v149, 0x160000, v149
	v_mul_u32_u24_e32 v150, 0x15d400, v144
	v_lshlrev_b32_e32 v142, 3, v141
	v_add3_u32 v128, v149, v150, v142
	v_cmp_eq_u32_e64 s[72:73], 0, v129
	v_cmp_eq_u32_e64 s[74:75], 3, v129
	s_and_b64 s[72:73], s[72:73], s[36:37]
	s_and_b64 s[74:75], s[74:75], s[54:55]
	s_or_b64 vcc, s[72:73], s[74:75]
	v_cndmask_b32_e32 v146, v146, v148, vcc
	global_load_dwordx4 v[88:91], v146, s[6:7]
	global_load_dwordx4 v[92:95], v147, s[0:1]
	global_load_dwordx4 v[96:99], v145, s[2:3]
	global_load_dwordx4 v[100:103], v145, s[4:5]
	v_add_u32_e32 v140, 0xa00, v202
	v_mul_hi_u32 v131, v140, s27
	v_mul_u32_u24_e32 v142, 0x580, v131
	v_sub_u32_e32 v141, v140, v142
	v_mul_u32_u24_e32 v142, 0x5800, v131
	v_lshl_add_u32 v145, v141, 4, v142
	v_and_b32_e32 v144, 1, v131
	v_mul_u32_u24_e32 v143, 0xb000, v144
	v_add_u32_e32 v146, v143, v145
	v_add_u32_e32 v148, 0x5800, v145
	v_lshl_add_u32 v147, v141, 4, v143
	v_lshrrev_b32_e32 v149, 1, v131
	v_mul_u32_u24_e32 v149, 0x160000, v149
	v_mul_u32_u24_e32 v150, 0x15d400, v144
	v_lshlrev_b32_e32 v142, 3, v141
	v_add3_u32 v130, v149, v150, v142
	v_cmp_eq_u32_e64 s[72:73], 0, v131
	v_cmp_eq_u32_e64 s[74:75], 3, v131
	s_and_b64 s[72:73], s[72:73], s[36:37]
	s_and_b64 s[74:75], s[74:75], s[54:55]
	s_or_b64 vcc, s[72:73], s[74:75]
	v_cndmask_b32_e32 v146, v146, v148, vcc
	global_load_dwordx4 v[104:107], v146, s[6:7]
	global_load_dwordx4 v[108:111], v147, s[0:1]
	global_load_dwordx4 v[112:115], v145, s[2:3]
	global_load_dwordx4 v[116:119], v145, s[4:5]
	s_waitcnt vmcnt(0)
; DI float silu(float v) { return v * __builtin_amdgcn_rcpf(1.f + __builtin_amdgcn_exp2f(-1.4426950408889634f * v)); }
; DI void st_bf16x4(bf16_t* p, f32x4 v) { u32x2 w; w.x = cvt_pk_bf16(v[0], v[1]); w.y = cvt_pk_bf16(v[2], v[3]); *(u32x2*)p = w; }
; DI void glu_fix_panel(const Params& p, int l, int pm) {
;     ...
;         f32x4 nb = (f32x4){0.f, 0.f, 0.f, 0.f}; int tap; int tok;
;         if (e == 0) { tap = 0; tok = 0; if (!(pr == 0 || pr == 1)) nb = *(const f32x4*)(EA + ((size_t)(pm - 1) * 4 + 3) * DFF + col); }
;         else if (e == 1) { tap = 2; tok = 127; nb = *(const f32x4*)(EA + ((size_t)pm * 4 + 2) * DFF + col); }
;         else if (e == 2) { tap = 0; tok = 128; nb = *(const f32x4*)(EA + ((size_t)pm * 4 + 1) * DFF + col); }
;         else { tap = 2; tok = 255; if (!(pr == 0 || pr == 8)) nb = *(const f32x4*)(EA + ((size_t)(pm + 1) * 4 + 0) * DFF + col); }
;         const f32x4 w = *(const f32x4*)(cw + (size_t)tap * DFF + col);
;         const size_t eo = ((size_t)pm * 4 + e) * DFF + col;
;         const f32x4 pp = *(const f32x4*)(EP + eo), uu = *(const f32x4*)(EU + eo);
;         f32x4 g;
; #pragma unroll
;         for (int j = 0; j < 4; ++j) g[j] = silu(pp[j] + w[j] * nb[j]) * uu[j];
;         st_bf16x4(G + ((size_t)pm * BM + tok) * DFF + col, g);
	v_cmp_eq_u32_e64 s[72:73], 0, v121
	v_cmp_eq_u32_e64 s[74:75], 3, v121
	s_and_b64 s[72:73], s[72:73], s[36:37]
	s_and_b64 s[74:75], s[74:75], s[54:55]
	s_or_b64 vcc, s[72:73], s[74:75]
	v_cndmask_b32_e64 v12, v12, 0, vcc
	v_cndmask_b32_e64 v13, v13, 0, vcc
	v_cndmask_b32_e64 v14, v14, 0, vcc
	v_cndmask_b32_e64 v15, v15, 0, vcc
	v_fmac_f32_e32 v20, v16, v12
	v_fmac_f32_e32 v21, v17, v13
	v_fmac_f32_e32 v22, v18, v14
	v_fmac_f32_e32 v23, v19, v15
	v_mul_f32_e32 v12, 0xbfb8aa3b, v20
	v_mul_f32_e32 v13, 0xbfb8aa3b, v21
	v_mul_f32_e32 v14, 0xbfb8aa3b, v22
	v_mul_f32_e32 v15, 0xbfb8aa3b, v23
	v_exp_f32_e32 v12, v12
	v_exp_f32_e32 v13, v13
	v_exp_f32_e32 v14, v14
	v_exp_f32_e32 v15, v15
	v_add_f32_e32 v12, 1.0, v12
	v_add_f32_e32 v13, 1.0, v13
	v_add_f32_e32 v14, 1.0, v14
	v_add_f32_e32 v15, 1.0, v15
	v_rcp_f32_e32 v12, v12
	v_rcp_f32_e32 v13, v13
	v_rcp_f32_e32 v14, v14
	v_rcp_f32_e32 v15, v15
	v_mul_f32_e32 v12, v20, v12
	v_mul_f32_e32 v13, v21, v13
	v_mul_f32_e32 v14, v22, v14
	v_mul_f32_e32 v15, v23, v15
	v_mul_f32_e32 v12, v24, v12
	v_mul_f32_e32 v13, v25, v13
	v_mul_f32_e32 v14, v26, v14
	v_mul_f32_e32 v15, v27, v15
	v_cvt_pk_bf16_f32 v12, v12, v13
	v_cvt_pk_bf16_f32 v13, v14, v15
	global_store_dwordx2 v120, v[12:13], s[22:23]
	v_cmp_eq_u32_e64 s[72:73], 0, v123
	v_cmp_eq_u32_e64 s[74:75], 3, v123
	s_and_b64 s[72:73], s[72:73], s[36:37]
	s_and_b64 s[74:75], s[74:75], s[54:55]
	s_or_b64 vcc, s[72:73], s[74:75]
	v_cndmask_b32_e64 v28, v28, 0, vcc
	v_cndmask_b32_e64 v29, v29, 0, vcc
	v_cndmask_b32_e64 v30, v30, 0, vcc
	v_cndmask_b32_e64 v31, v31, 0, vcc
	v_fmac_f32_e32 v36, v32, v28
	v_fmac_f32_e32 v37, v33, v29
	v_fmac_f32_e32 v38, v34, v30
	v_fmac_f32_e32 v39, v35, v31
	v_mul_f32_e32 v28, 0xbfb8aa3b, v36
	v_mul_f32_e32 v29, 0xbfb8aa3b, v37
	v_mul_f32_e32 v30, 0xbfb8aa3b, v38
	v_mul_f32_e32 v31, 0xbfb8aa3b, v39
	v_exp_f32_e32 v28, v28
	v_exp_f32_e32 v29, v29
	v_exp_f32_e32 v30, v30
	v_exp_f32_e32 v31, v31
	v_add_f32_e32 v28, 1.0, v28
	v_add_f32_e32 v29, 1.0, v29
	v_add_f32_e32 v30, 1.0, v30
	v_add_f32_e32 v31, 1.0, v31
	v_rcp_f32_e32 v28, v28
	v_rcp_f32_e32 v29, v29
	v_rcp_f32_e32 v30, v30
	v_rcp_f32_e32 v31, v31
	v_mul_f32_e32 v28, v36, v28
	v_mul_f32_e32 v29, v37, v29
	v_mul_f32_e32 v30, v38, v30
	v_mul_f32_e32 v31, v39, v31
	v_mul_f32_e32 v28, v40, v28
	v_mul_f32_e32 v29, v41, v29
	v_mul_f32_e32 v30, v42, v30
	v_mul_f32_e32 v31, v43, v31
	v_cvt_pk_bf16_f32 v28, v28, v29
	v_cvt_pk_bf16_f32 v29, v30, v31
	global_store_dwordx2 v122, v[28:29], s[22:23]
	v_cmp_eq_u32_e64 s[72:73], 0, v125
	v_cmp_eq_u32_e64 s[74:75], 3, v125
	s_and_b64 s[72:73], s[72:73], s[36:37]
	s_and_b64 s[74:75], s[74:75], s[54:55]
	s_or_b64 vcc, s[72:73], s[74:75]
	v_cndmask_b32_e64 v44, v44, 0, vcc
	v_cndmask_b32_e64 v45, v45, 0, vcc
	v_cndmask_b32_e64 v46, v46, 0, vcc
	v_cndmask_b32_e64 v47, v47, 0, vcc
	v_fmac_f32_e32 v52, v48, v44
	v_fmac_f32_e32 v53, v49, v45
	v_fmac_f32_e32 v54, v50, v46
	v_fmac_f32_e32 v55, v51, v47
	v_mul_f32_e32 v44, 0xbfb8aa3b, v52
	v_mul_f32_e32 v45, 0xbfb8aa3b, v53
	v_mul_f32_e32 v46, 0xbfb8aa3b, v54
	v_mul_f32_e32 v47, 0xbfb8aa3b, v55
	v_exp_f32_e32 v44, v44
	v_exp_f32_e32 v45, v45
	v_exp_f32_e32 v46, v46
	v_exp_f32_e32 v47, v47
	v_add_f32_e32 v44, 1.0, v44
	v_add_f32_e32 v45, 1.0, v45
	v_add_f32_e32 v46, 1.0, v46
	v_add_f32_e32 v47, 1.0, v47
	v_rcp_f32_e32 v44, v44
	v_rcp_f32_e32 v45, v45
	v_rcp_f32_e32 v46, v46
	v_rcp_f32_e32 v47, v47
	v_mul_f32_e32 v44, v52, v44
	v_mul_f32_e32 v45, v53, v45
	v_mul_f32_e32 v46, v54, v46
	v_mul_f32_e32 v47, v55, v47
	v_mul_f32_e32 v44, v56, v44
	v_mul_f32_e32 v45, v57, v45
	v_mul_f32_e32 v46, v58, v46
	v_mul_f32_e32 v47, v59, v47
	v_cvt_pk_bf16_f32 v44, v44, v45
	v_cvt_pk_bf16_f32 v45, v46, v47
	global_store_dwordx2 v124, v[44:45], s[22:23]
	v_cmp_eq_u32_e64 s[72:73], 0, v127
	v_cmp_eq_u32_e64 s[74:75], 3, v127
	s_and_b64 s[72:73], s[72:73], s[36:37]
	s_and_b64 s[74:75], s[74:75], s[54:55]
	s_or_b64 vcc, s[72:73], s[74:75]
	v_cndmask_b32_e64 v60, v60, 0, vcc
	v_cndmask_b32_e64 v61, v61, 0, vcc
	v_cndmask_b32_e64 v62, v62, 0, vcc
	v_cndmask_b32_e64 v63, v63, 0, vcc
	v_fmac_f32_e32 v68, v64, v60
	v_fmac_f32_e32 v69, v65, v61
	v_fmac_f32_e32 v70, v66, v62
	v_fmac_f32_e32 v71, v67, v63
	v_mul_f32_e32 v60, 0xbfb8aa3b, v68
	v_mul_f32_e32 v61, 0xbfb8aa3b, v69
	v_mul_f32_e32 v62, 0xbfb8aa3b, v70
	v_mul_f32_e32 v63, 0xbfb8aa3b, v71
	v_exp_f32_e32 v60, v60
	v_exp_f32_e32 v61, v61
	v_exp_f32_e32 v62, v62
	v_exp_f32_e32 v63, v63
	v_add_f32_e32 v60, 1.0, v60
	v_add_f32_e32 v61, 1.0, v61
	v_add_f32_e32 v62, 1.0, v62
	v_add_f32_e32 v63, 1.0, v63
	v_rcp_f32_e32 v60, v60
	v_rcp_f32_e32 v61, v61
	v_rcp_f32_e32 v62, v62
	v_rcp_f32_e32 v63, v63
	v_mul_f32_e32 v60, v68, v60
	v_mul_f32_e32 v61, v69, v61
	v_mul_f32_e32 v62, v70, v62
	v_mul_f32_e32 v63, v71, v63
	v_mul_f32_e32 v60, v72, v60
	v_mul_f32_e32 v61, v73, v61
	v_mul_f32_e32 v62, v74, v62
	v_mul_f32_e32 v63, v75, v63
	v_cvt_pk_bf16_f32 v60, v60, v61
	v_cvt_pk_bf16_f32 v61, v62, v63
	global_store_dwordx2 v126, v[60:61], s[22:23]
	v_cmp_eq_u32_e64 s[72:73], 0, v129
	v_cmp_eq_u32_e64 s[74:75], 3, v129
	s_and_b64 s[72:73], s[72:73], s[36:37]
	s_and_b64 s[74:75], s[74:75], s[54:55]
	s_or_b64 vcc, s[72:73], s[74:75]
	v_cndmask_b32_e64 v88, v88, 0, vcc
	v_cndmask_b32_e64 v89, v89, 0, vcc
	v_cndmask_b32_e64 v90, v90, 0, vcc
	v_cndmask_b32_e64 v91, v91, 0, vcc
	v_fmac_f32_e32 v96, v92, v88
	v_fmac_f32_e32 v97, v93, v89
	v_fmac_f32_e32 v98, v94, v90
	v_fmac_f32_e32 v99, v95, v91
	v_mul_f32_e32 v88, 0xbfb8aa3b, v96
	v_mul_f32_e32 v89, 0xbfb8aa3b, v97
	v_mul_f32_e32 v90, 0xbfb8aa3b, v98
	v_mul_f32_e32 v91, 0xbfb8aa3b, v99
	v_exp_f32_e32 v88, v88
	v_exp_f32_e32 v89, v89
; DI float silu(float v) { return v * __builtin_amdgcn_rcpf(1.f + __builtin_amdgcn_exp2f(-1.4426950408889634f * v)); }
; DI void st_bf16x4(bf16_t* p, f32x4 v) { u32x2 w; w.x = cvt_pk_bf16(v[0], v[1]); w.y = cvt_pk_bf16(v[2], v[3]); *(u32x2*)p = w; }
; DI void glu_fix_panel(const Params& p, int l, int pm) {
;     ...
;     for (int it = tid_; it < 4 * (DFF / 4); it += 512) {
;         const int col = (it % (DFF / 4)) * 4, e = it / (DFF / 4);
;         f32x4 nb = (f32x4){0.f, 0.f, 0.f, 0.f}; int tap; int tok;
;         if (e == 0) { tap = 0; tok = 0; if (!(pr == 0 || pr == 1)) nb = *(const f32x4*)(EA + ((size_t)(pm - 1) * 4 + 3) * DFF + col); }
;         else if (e == 1) { tap = 2; tok = 127; nb = *(const f32x4*)(EA + ((size_t)pm * 4 + 2) * DFF + col); }
;         else if (e == 2) { tap = 0; tok = 128; nb = *(const f32x4*)(EA + ((size_t)pm * 4 + 1) * DFF + col); }
;         else { tap = 2; tok = 255; if (!(pr == 0 || pr == 8)) nb = *(const f32x4*)(EA + ((size_t)(pm + 1) * 4 + 0) * DFF + col); }
;         const f32x4 w = *(const f32x4*)(cw + (size_t)tap * DFF + col);
;         const size_t eo = ((size_t)pm * 4 + e) * DFF + col;
;         const f32x4 pp = *(const f32x4*)(EP + eo), uu = *(const f32x4*)(EU + eo);
;         f32x4 g;
; #pragma unroll
;         for (int j = 0; j < 4; ++j) g[j] = silu(pp[j] + w[j] * nb[j]) * uu[j];
;         st_bf16x4(G + ((size_t)pm * BM + tok) * DFF + col, g);
	v_exp_f32_e32 v90, v90
	v_exp_f32_e32 v91, v91
	v_add_f32_e32 v88, 1.0, v88
	v_add_f32_e32 v89, 1.0, v89
	v_add_f32_e32 v90, 1.0, v90
	v_add_f32_e32 v91, 1.0, v91
	v_rcp_f32_e32 v88, v88
	v_rcp_f32_e32 v89, v89
	v_rcp_f32_e32 v90, v90
	v_rcp_f32_e32 v91, v91
	v_mul_f32_e32 v88, v96, v88
	v_mul_f32_e32 v89, v97, v89
	v_mul_f32_e32 v90, v98, v90
	v_mul_f32_e32 v91, v99, v91
	v_mul_f32_e32 v88, v100, v88
	v_mul_f32_e32 v89, v101, v89
	v_mul_f32_e32 v90, v102, v90
	v_mul_f32_e32 v91, v103, v91
	v_cvt_pk_bf16_f32 v88, v88, v89
	v_cvt_pk_bf16_f32 v89, v90, v91
	global_store_dwordx2 v128, v[88:89], s[22:23]
	v_cmp_eq_u32_e64 s[72:73], 0, v131
	v_cmp_eq_u32_e64 s[74:75], 3, v131
	s_and_b64 s[72:73], s[72:73], s[36:37]
	s_and_b64 s[74:75], s[74:75], s[54:55]
	s_or_b64 vcc, s[72:73], s[74:75]
	v_cndmask_b32_e64 v104, v104, 0, vcc
	v_cndmask_b32_e64 v105, v105, 0, vcc
	v_cndmask_b32_e64 v106, v106, 0, vcc
	v_cndmask_b32_e64 v107, v107, 0, vcc
	v_fmac_f32_e32 v112, v108, v104
	v_fmac_f32_e32 v113, v109, v105
	v_fmac_f32_e32 v114, v110, v106
	v_fmac_f32_e32 v115, v111, v107
	v_mul_f32_e32 v104, 0xbfb8aa3b, v112
	v_mul_f32_e32 v105, 0xbfb8aa3b, v113
	v_mul_f32_e32 v106, 0xbfb8aa3b, v114
	v_mul_f32_e32 v107, 0xbfb8aa3b, v115
	v_exp_f32_e32 v104, v104
	v_exp_f32_e32 v105, v105
	v_exp_f32_e32 v106, v106
	v_exp_f32_e32 v107, v107
	v_add_f32_e32 v104, 1.0, v104
	v_add_f32_e32 v105, 1.0, v105
	v_add_f32_e32 v106, 1.0, v106
	v_add_f32_e32 v107, 1.0, v107
	v_rcp_f32_e32 v104, v104
	v_rcp_f32_e32 v105, v105
	v_rcp_f32_e32 v106, v106
	v_rcp_f32_e32 v107, v107
	v_mul_f32_e32 v104, v112, v104
	v_mul_f32_e32 v105, v113, v105
	v_mul_f32_e32 v106, v114, v106
	v_mul_f32_e32 v107, v115, v107
	v_mul_f32_e32 v104, v116, v104
	v_mul_f32_e32 v105, v117, v105
	v_mul_f32_e32 v106, v118, v106
	v_mul_f32_e32 v107, v119, v107
	v_cvt_pk_bf16_f32 v104, v104, v105
	v_cvt_pk_bf16_f32 v105, v106, v107
	global_store_dwordx2 v130, v[104:105], s[22:23]
	v_add_u32_e32 v140, 0xc00, v202
	v_mul_hi_u32 v121, v140, s27
	v_mul_u32_u24_e32 v142, 0x580, v121
	v_sub_u32_e32 v141, v140, v142
	v_mul_u32_u24_e32 v142, 0x5800, v121
	v_lshl_add_u32 v145, v141, 4, v142
	v_and_b32_e32 v144, 1, v121
	v_mul_u32_u24_e32 v143, 0xb000, v144
	v_add_u32_e32 v146, v143, v145
	v_add_u32_e32 v148, 0x5800, v145
	v_lshl_add_u32 v147, v141, 4, v143
	v_lshrrev_b32_e32 v149, 1, v121
	v_mul_u32_u24_e32 v149, 0x160000, v149
	v_mul_u32_u24_e32 v150, 0x15d400, v144
	v_lshlrev_b32_e32 v142, 3, v141
	v_add3_u32 v120, v149, v150, v142
	v_cmp_eq_u32_e64 s[72:73], 0, v121
	v_cmp_eq_u32_e64 s[74:75], 3, v121
	s_and_b64 s[72:73], s[72:73], s[36:37]
	s_and_b64 s[74:75], s[74:75], s[54:55]
	s_or_b64 vcc, s[72:73], s[74:75]
	v_cndmask_b32_e32 v146, v146, v148, vcc
	global_load_dwordx4 v[12:15], v146, s[6:7]
	global_load_dwordx4 v[16:19], v147, s[0:1]
	global_load_dwordx4 v[20:23], v145, s[2:3]
	global_load_dwordx4 v[24:27], v145, s[4:5]
	v_add_u32_e32 v140, 0xe00, v202
	v_mul_hi_u32 v123, v140, s27
	v_mul_u32_u24_e32 v142, 0x580, v123
	v_sub_u32_e32 v141, v140, v142
	v_mul_u32_u24_e32 v142, 0x5800, v123
	v_lshl_add_u32 v145, v141, 4, v142
	v_and_b32_e32 v144, 1, v123
	v_mul_u32_u24_e32 v143, 0xb000, v144
	v_add_u32_e32 v146, v143, v145
	v_add_u32_e32 v148, 0x5800, v145
	v_lshl_add_u32 v147, v141, 4, v143
	v_lshrrev_b32_e32 v149, 1, v123
	v_mul_u32_u24_e32 v149, 0x160000, v149
	v_mul_u32_u24_e32 v150, 0x15d400, v144
	v_lshlrev_b32_e32 v142, 3, v141
	v_add3_u32 v122, v149, v150, v142
	v_cmp_eq_u32_e64 s[72:73], 0, v123
	v_cmp_eq_u32_e64 s[74:75], 3, v123
	s_and_b64 s[72:73], s[72:73], s[36:37]
	s_and_b64 s[74:75], s[74:75], s[54:55]
	s_or_b64 vcc, s[72:73], s[74:75]
	v_cndmask_b32_e32 v146, v146, v148, vcc
	global_load_dwordx4 v[28:31], v146, s[6:7]
	global_load_dwordx4 v[32:35], v147, s[0:1]
	global_load_dwordx4 v[36:39], v145, s[2:3]
	global_load_dwordx4 v[40:43], v145, s[4:5]
	v_add_u32_e32 v140, 0x1000, v202
	v_mul_hi_u32 v125, v140, s27
	v_mul_u32_u24_e32 v142, 0x580, v125
	v_sub_u32_e32 v141, v140, v142
	v_mul_u32_u24_e32 v142, 0x5800, v125
	v_lshl_add_u32 v145, v141, 4, v142
	v_and_b32_e32 v144, 1, v125
	v_mul_u32_u24_e32 v143, 0xb000, v144
	v_add_u32_e32 v146, v143, v145
	v_add_u32_e32 v148, 0x5800, v145
	v_lshl_add_u32 v147, v141, 4, v143
	v_lshrrev_b32_e32 v149, 1, v125
	v_mul_u32_u24_e32 v149, 0x160000, v149
	v_mul_u32_u24_e32 v150, 0x15d400, v144
	v_lshlrev_b32_e32 v142, 3, v141
	v_add3_u32 v124, v149, v150, v142
	v_cmp_eq_u32_e64 s[72:73], 0, v125
	v_cmp_eq_u32_e64 s[74:75], 3, v125
	s_and_b64 s[72:73], s[72:73], s[36:37]
	s_and_b64 s[74:75], s[74:75], s[54:55]
	s_or_b64 vcc, s[72:73], s[74:75]
	v_cndmask_b32_e32 v146, v146, v148, vcc
	global_load_dwordx4 v[44:47], v146, s[6:7]
	global_load_dwordx4 v[48:51], v147, s[0:1]
	global_load_dwordx4 v[52:55], v145, s[2:3]
	global_load_dwordx4 v[56:59], v145, s[4:5]
	v_add_u32_e32 v140, 0x1200, v202
	v_mul_hi_u32 v127, v140, s27
	v_mul_u32_u24_e32 v142, 0x580, v127
	v_sub_u32_e32 v141, v140, v142
	v_mul_u32_u24_e32 v142, 0x5800, v127
	v_lshl_add_u32 v145, v141, 4, v142
	v_and_b32_e32 v144, 1, v127
	v_mul_u32_u24_e32 v143, 0xb000, v144
	v_add_u32_e32 v146, v143, v145
	v_add_u32_e32 v148, 0x5800, v145
	v_lshl_add_u32 v147, v141, 4, v143
	v_lshrrev_b32_e32 v149, 1, v127
	v_mul_u32_u24_e32 v149, 0x160000, v149
	v_mul_u32_u24_e32 v150, 0x15d400, v144
	v_lshlrev_b32_e32 v142, 3, v141
	v_add3_u32 v126, v149, v150, v142
	v_cmp_eq_u32_e64 s[72:73], 0, v127
	v_cmp_eq_u32_e64 s[74:75], 3, v127
	s_and_b64 s[72:73], s[72:73], s[36:37]
	s_and_b64 s[74:75], s[74:75], s[54:55]
	s_or_b64 vcc, s[72:73], s[74:75]
	v_cndmask_b32_e32 v146, v146, v148, vcc
	global_load_dwordx4 v[60:63], v146, s[6:7]
	global_load_dwordx4 v[64:67], v147, s[0:1]
	global_load_dwordx4 v[68:71], v145, s[2:3]
	global_load_dwordx4 v[72:75], v145, s[4:5]
	v_add_u32_e32 v140, 0x1400, v202
	v_mul_hi_u32 v129, v140, s27
	v_mul_u32_u24_e32 v142, 0x580, v129
	v_sub_u32_e32 v141, v140, v142
	v_mul_u32_u24_e32 v142, 0x5800, v129
	v_lshl_add_u32 v145, v141, 4, v142
	v_and_b32_e32 v144, 1, v129
	v_mul_u32_u24_e32 v143, 0xb000, v144
	v_add_u32_e32 v146, v143, v145
	v_add_u32_e32 v148, 0x5800, v145
	v_lshl_add_u32 v147, v141, 4, v143
	v_lshrrev_b32_e32 v149, 1, v129
	v_mul_u32_u24_e32 v149, 0x160000, v149
	v_mul_u32_u24_e32 v150, 0x15d400, v144
	v_lshlrev_b32_e32 v142, 3, v141
	v_add3_u32 v128, v149, v150, v142
	v_cmp_eq_u32_e64 s[72:73], 0, v129
	v_cmp_eq_u32_e64 s[74:75], 3, v129
	s_and_b64 s[72:73], s[72:73], s[36:37]
	s_and_b64 s[74:75], s[74:75], s[54:55]
	s_or_b64 vcc, s[72:73], s[74:75]
	v_cndmask_b32_e32 v146, v146, v148, vcc
	global_load_dwordx4 v[88:91], v146, s[6:7]
	global_load_dwordx4 v[92:95], v147, s[0:1]
	global_load_dwordx4 v[96:99], v145, s[2:3]
	global_load_dwordx4 v[100:103], v145, s[4:5]
	s_waitcnt vmcnt(0)
; DI float silu(float v) { return v * __builtin_amdgcn_rcpf(1.f + __builtin_amdgcn_exp2f(-1.4426950408889634f * v)); }
; DI void st_bf16x4(bf16_t* p, f32x4 v) { u32x2 w; w.x = cvt_pk_bf16(v[0], v[1]); w.y = cvt_pk_bf16(v[2], v[3]); *(u32x2*)p = w; }
; DI void glu_fix_panel(const Params& p, int l, int pm) {
;     ...
;         f32x4 nb = (f32x4){0.f, 0.f, 0.f, 0.f}; int tap; int tok;
;         if (e == 0) { tap = 0; tok = 0; if (!(pr == 0 || pr == 1)) nb = *(const f32x4*)(EA + ((size_t)(pm - 1) * 4 + 3) * DFF + col); }
;         else if (e == 1) { tap = 2; tok = 127; nb = *(const f32x4*)(EA + ((size_t)pm * 4 + 2) * DFF + col); }
;         else if (e == 2) { tap = 0; tok = 128; nb = *(const f32x4*)(EA + ((size_t)pm * 4 + 1) * DFF + col); }
;         else { tap = 2; tok = 255; if (!(pr == 0 || pr == 8)) nb = *(const f32x4*)(EA + ((size_t)(pm + 1) * 4 + 0) * DFF + col); }
;         const f32x4 w = *(const f32x4*)(cw + (size_t)tap * DFF + col);
;         const size_t eo = ((size_t)pm * 4 + e) * DFF + col;
;         const f32x4 pp = *(const f32x4*)(EP + eo), uu = *(const f32x4*)(EU + eo);
;         f32x4 g;
; #pragma unroll
;         for (int j = 0; j < 4; ++j) g[j] = silu(pp[j] + w[j] * nb[j]) * uu[j];
;         st_bf16x4(G + ((size_t)pm * BM + tok) * DFF + col, g);
	v_cmp_eq_u32_e64 s[72:73], 0, v121
	v_cmp_eq_u32_e64 s[74:75], 3, v121
	s_and_b64 s[72:73], s[72:73], s[36:37]
	s_and_b64 s[74:75], s[74:75], s[54:55]
	s_or_b64 vcc, s[72:73], s[74:75]
	v_cndmask_b32_e64 v12, v12, 0, vcc
	v_cndmask_b32_e64 v13, v13, 0, vcc
	v_cndmask_b32_e64 v14, v14, 0, vcc
	v_cndmask_b32_e64 v15, v15, 0, vcc
	v_fmac_f32_e32 v20, v16, v12
	v_fmac_f32_e32 v21, v17, v13
	v_fmac_f32_e32 v22, v18, v14
	v_fmac_f32_e32 v23, v19, v15
	v_mul_f32_e32 v12, 0xbfb8aa3b, v20
	v_mul_f32_e32 v13, 0xbfb8aa3b, v21
	v_mul_f32_e32 v14, 0xbfb8aa3b, v22
	v_mul_f32_e32 v15, 0xbfb8aa3b, v23
	v_exp_f32_e32 v12, v12
	v_exp_f32_e32 v13, v13
	v_exp_f32_e32 v14, v14
	v_exp_f32_e32 v15, v15
	v_add_f32_e32 v12, 1.0, v12
	v_add_f32_e32 v13, 1.0, v13
	v_add_f32_e32 v14, 1.0, v14
	v_add_f32_e32 v15, 1.0, v15
	v_rcp_f32_e32 v12, v12
	v_rcp_f32_e32 v13, v13
	v_rcp_f32_e32 v14, v14
	v_rcp_f32_e32 v15, v15
	v_mul_f32_e32 v12, v20, v12
	v_mul_f32_e32 v13, v21, v13
	v_mul_f32_e32 v14, v22, v14
	v_mul_f32_e32 v15, v23, v15
	v_mul_f32_e32 v12, v24, v12
	v_mul_f32_e32 v13, v25, v13
	v_mul_f32_e32 v14, v26, v14
	v_mul_f32_e32 v15, v27, v15
	v_cvt_pk_bf16_f32 v12, v12, v13
	v_cvt_pk_bf16_f32 v13, v14, v15
	global_store_dwordx2 v120, v[12:13], s[22:23]
	v_cmp_eq_u32_e64 s[72:73], 0, v123
	v_cmp_eq_u32_e64 s[74:75], 3, v123
	s_and_b64 s[72:73], s[72:73], s[36:37]
	s_and_b64 s[74:75], s[74:75], s[54:55]
	s_or_b64 vcc, s[72:73], s[74:75]
	v_cndmask_b32_e64 v28, v28, 0, vcc
	v_cndmask_b32_e64 v29, v29, 0, vcc
	v_cndmask_b32_e64 v30, v30, 0, vcc
	v_cndmask_b32_e64 v31, v31, 0, vcc
	v_fmac_f32_e32 v36, v32, v28
	v_fmac_f32_e32 v37, v33, v29
	v_fmac_f32_e32 v38, v34, v30
	v_fmac_f32_e32 v39, v35, v31
	v_mul_f32_e32 v28, 0xbfb8aa3b, v36
	v_mul_f32_e32 v29, 0xbfb8aa3b, v37
	v_mul_f32_e32 v30, 0xbfb8aa3b, v38
	v_mul_f32_e32 v31, 0xbfb8aa3b, v39
	v_exp_f32_e32 v28, v28
	v_exp_f32_e32 v29, v29
	v_exp_f32_e32 v30, v30
	v_exp_f32_e32 v31, v31
	v_add_f32_e32 v28, 1.0, v28
	v_add_f32_e32 v29, 1.0, v29
	v_add_f32_e32 v30, 1.0, v30
	v_add_f32_e32 v31, 1.0, v31
	v_rcp_f32_e32 v28, v28
	v_rcp_f32_e32 v29, v29
	v_rcp_f32_e32 v30, v30
	v_rcp_f32_e32 v31, v31
	v_mul_f32_e32 v28, v36, v28
	v_mul_f32_e32 v29, v37, v29
	v_mul_f32_e32 v30, v38, v30
	v_mul_f32_e32 v31, v39, v31
	v_mul_f32_e32 v28, v40, v28
	v_mul_f32_e32 v29, v41, v29
	v_mul_f32_e32 v30, v42, v30
	v_mul_f32_e32 v31, v43, v31
	v_cvt_pk_bf16_f32 v28, v28, v29
	v_cvt_pk_bf16_f32 v29, v30, v31
	global_store_dwordx2 v122, v[28:29], s[22:23]
	v_cmp_eq_u32_e64 s[72:73], 0, v125
	v_cmp_eq_u32_e64 s[74:75], 3, v125
	s_and_b64 s[72:73], s[72:73], s[36:37]
	s_and_b64 s[74:75], s[74:75], s[54:55]
	s_or_b64 vcc, s[72:73], s[74:75]
	v_cndmask_b32_e64 v44, v44, 0, vcc
	v_cndmask_b32_e64 v45, v45, 0, vcc
	v_cndmask_b32_e64 v46, v46, 0, vcc
	v_cndmask_b32_e64 v47, v47, 0, vcc
	v_fmac_f32_e32 v52, v48, v44
	v_fmac_f32_e32 v53, v49, v45
	v_fmac_f32_e32 v54, v50, v46
	v_fmac_f32_e32 v55, v51, v47
	v_mul_f32_e32 v44, 0xbfb8aa3b, v52
	v_mul_f32_e32 v45, 0xbfb8aa3b, v53
	v_mul_f32_e32 v46, 0xbfb8aa3b, v54
	v_mul_f32_e32 v47, 0xbfb8aa3b, v55
	v_exp_f32_e32 v44, v44
	v_exp_f32_e32 v45, v45
	v_exp_f32_e32 v46, v46
	v_exp_f32_e32 v47, v47
	v_add_f32_e32 v44, 1.0, v44
	v_add_f32_e32 v45, 1.0, v45
	v_add_f32_e32 v46, 1.0, v46
	v_add_f32_e32 v47, 1.0, v47
	v_rcp_f32_e32 v44, v44
	v_rcp_f32_e32 v45, v45
	v_rcp_f32_e32 v46, v46
	v_rcp_f32_e32 v47, v47
	v_mul_f32_e32 v44, v52, v44
	v_mul_f32_e32 v45, v53, v45
	v_mul_f32_e32 v46, v54, v46
	v_mul_f32_e32 v47, v55, v47
	v_mul_f32_e32 v44, v56, v44
	v_mul_f32_e32 v45, v57, v45
	v_mul_f32_e32 v46, v58, v46
	v_mul_f32_e32 v47, v59, v47
	v_cvt_pk_bf16_f32 v44, v44, v45
	v_cvt_pk_bf16_f32 v45, v46, v47
	global_store_dwordx2 v124, v[44:45], s[22:23]
	v_cmp_eq_u32_e64 s[72:73], 0, v127
	v_cmp_eq_u32_e64 s[74:75], 3, v127
	s_and_b64 s[72:73], s[72:73], s[36:37]
	s_and_b64 s[74:75], s[74:75], s[54:55]
	s_or_b64 vcc, s[72:73], s[74:75]
	v_cndmask_b32_e64 v60, v60, 0, vcc
	v_cndmask_b32_e64 v61, v61, 0, vcc
	v_cndmask_b32_e64 v62, v62, 0, vcc
	v_cndmask_b32_e64 v63, v63, 0, vcc
	v_fmac_f32_e32 v68, v64, v60
	v_fmac_f32_e32 v69, v65, v61
	v_fmac_f32_e32 v70, v66, v62
	v_fmac_f32_e32 v71, v67, v63
	v_mul_f32_e32 v60, 0xbfb8aa3b, v68
	v_mul_f32_e32 v61, 0xbfb8aa3b, v69
	v_mul_f32_e32 v62, 0xbfb8aa3b, v70
	v_mul_f32_e32 v63, 0xbfb8aa3b, v71
	v_exp_f32_e32 v60, v60
	v_exp_f32_e32 v61, v61
	v_exp_f32_e32 v62, v62
	v_exp_f32_e32 v63, v63
	v_add_f32_e32 v60, 1.0, v60
	v_add_f32_e32 v61, 1.0, v61
	v_add_f32_e32 v62, 1.0, v62
	v_add_f32_e32 v63, 1.0, v63
	v_rcp_f32_e32 v60, v60
	v_rcp_f32_e32 v61, v61
	v_rcp_f32_e32 v62, v62
	v_rcp_f32_e32 v63, v63
	v_mul_f32_e32 v60, v68, v60
	v_mul_f32_e32 v61, v69, v61
	v_mul_f32_e32 v62, v70, v62
	v_mul_f32_e32 v63, v71, v63
	v_mul_f32_e32 v60, v72, v60
	v_mul_f32_e32 v61, v73, v61
	v_mul_f32_e32 v62, v74, v62
	v_mul_f32_e32 v63, v75, v63
	v_cvt_pk_bf16_f32 v60, v60, v61
	v_cvt_pk_bf16_f32 v61, v62, v63
	global_store_dwordx2 v126, v[60:61], s[22:23]
	v_cmp_eq_u32_e64 s[72:73], 0, v129
	v_cmp_eq_u32_e64 s[74:75], 3, v129
	s_and_b64 s[72:73], s[72:73], s[36:37]
	s_and_b64 s[74:75], s[74:75], s[54:55]
	s_or_b64 vcc, s[72:73], s[74:75]
	v_cndmask_b32_e64 v88, v88, 0, vcc
	v_cndmask_b32_e64 v89, v89, 0, vcc
	v_cndmask_b32_e64 v90, v90, 0, vcc
	v_cndmask_b32_e64 v91, v91, 0, vcc
	v_fmac_f32_e32 v96, v92, v88
	v_fmac_f32_e32 v97, v93, v89
	v_fmac_f32_e32 v98, v94, v90
	v_fmac_f32_e32 v99, v95, v91
	v_mul_f32_e32 v88, 0xbfb8aa3b, v96
	v_mul_f32_e32 v89, 0xbfb8aa3b, v97
	v_mul_f32_e32 v90, 0xbfb8aa3b, v98
	v_mul_f32_e32 v91, 0xbfb8aa3b, v99
	v_exp_f32_e32 v88, v88
	v_exp_f32_e32 v89, v89
	v_exp_f32_e32 v90, v90
	v_exp_f32_e32 v91, v91
	v_add_f32_e32 v88, 1.0, v88
	v_add_f32_e32 v89, 1.0, v89
	v_add_f32_e32 v90, 1.0, v90
	v_add_f32_e32 v91, 1.0, v91
	v_rcp_f32_e32 v88, v88
	v_rcp_f32_e32 v89, v89
	v_rcp_f32_e32 v90, v90
	v_rcp_f32_e32 v91, v91
	v_mul_f32_e32 v88, v96, v88
	v_mul_f32_e32 v89, v97, v89
	v_mul_f32_e32 v90, v98, v90
	v_mul_f32_e32 v91, v99, v91
	v_mul_f32_e32 v88, v100, v88
	v_mul_f32_e32 v89, v101, v89
	v_mul_f32_e32 v90, v102, v90
	v_mul_f32_e32 v91, v103, v91
	v_cvt_pk_bf16_f32 v88, v88, v89
	v_cvt_pk_bf16_f32 v89, v90, v91
	global_store_dwordx2 v128, v[88:89], s[22:23]
